# EpiZ (w_in GEMM epilogue) hand-packed: packed gelu with folded constants, batched LayerNorm-stat reduction
# baseline (speedup 1.0000x reference)
; __device__ __forceinline__ void row_rs8(const float* SS, int row0, int fq, float (&rsv)[2][4]) {
;     f32x4 q[2][4];
; #pragma unroll
;     for (int ai = 0; ai < 2; ++ai)
; #pragma unroll
;         for (int m = 0; m < 4; ++m) q[ai][m] = *(const f32x4*)(SS + (size_t)(row0 + ai * HALF + m * 16) * 16 + 4 * fq);
; #pragma unroll
;     for (int ai = 0; ai < 2; ++ai)
; #pragma unroll
;         for (int m = 0; m < 4; ++m) { float t = (q[ai][m][0] + q[ai][m][1]) + (q[ai][m][2] + q[ai][m][3]); t += __shfl_xor(t, 16); t += __shfl_xor(t, 32); rsv[ai][m] = __builtin_amdgcn_rsqf(t * (1.0f / 1024.0f) + 1e-6f); }
; }
;     __device__ __forceinline__ void operator()(const f32x4 (&acc)[2][2][4][2], const Unit& u, int wr, int wc, int fr, int fq) const {
;         const int row0 = u.pm * BM + wr * 64 + fr, col0 = u.pn * BM + wc * 32 + 8 * fq;
;         float rsv[2][4]; row_rs8(SS, row0, fq, rsv);
;         const bool va_tile = (u.pn == 2 || u.pn == 3);
; #pragma unroll
;         for (int ai = 0; ai < 2; ++ai)
; #pragma unroll
;             for (int m = 0; m < 4; ++m) {
;                 const int r = row0 + ai * HALF + m * 16; const float rs = rsv[ai][m];
;                 float s1 = 0.f, s2 = 0.f;
; #pragma unroll
;                 for (int bj = 0; bj < 2; ++bj) {
;                     f32x4 a = acc[ai][bj][m][0] * rs, b = acc[ai][bj][m][1] * rs;
;                     if (u.pn < gelu_tiles) {
; #pragma unroll
;                         for (int j = 0; j < 4; ++j) { const float ua = 1.5957691216057308f * a[j] * (1.0f + 0.044715f * a[j] * a[j]), ub = 1.5957691216057308f * b[j] * (1.0f + 0.044715f * b[j] * b[j]);
;                             a[j] = a[j] * fast_rcp(1.0f + __expf(-ua)); b[j] = b[j] * fast_rcp(1.0f + __expf(-ub)); }
;                     }
;                     if (va_tile) {
;                         s1 += ((a[0] + a[1]) + (a[2] + a[3])) + ((b[0] + b[1]) + (b[2] + b[3]));
;                         s2 += ((a[0] * a[0] + a[1] * a[1]) + (a[2] * a[2] + a[3] * a[3])) + ((b[0] * b[0] + b[1] * b[1]) + (b[2] * b[2] + b[3] * b[3]));
;                     }
;                     u32x4 w; w.x = cvt_pk_bf16(a[0], a[1]); w.y = cvt_pk_bf16(a[2], a[3]); w.z = cvt_pk_bf16(b[0], b[1]); w.w = cvt_pk_bf16(b[2], b[3]);
;                     *(u32x4*)(O + (size_t)r * ldo + col0 + bj * HALF) = w;
.LBB0_476:
	v_lshl_add_u32 v208, s4, 8, v129
	v_mov_b32_e32 v209, 0
	v_or_b32_e32 v225, 16, v208
	v_or_b32_e32 v227, 32, v208
	v_or_b32_e32 v229, 48, v208
	v_add_u32_e32 v231, 0x80, v208
	v_add_u32_e32 v233, 0x90, v208
	v_add_u32_e32 v235, 0xa0, v208
	v_add_u32_e32 v236, 0xb0, v208
	v_lshlrev_b32_e32 v216, 6, v208
	v_mov_b32_e32 v217, 0
	v_lshl_add_u64 v[214:215], v[140:141], 0, v[216:217]
	s_movk_i32 s84, 0x2000
	s_mov_b32 s85, 0
	v_lshl_add_u64 v[216:217], v[214:215], 0, s[84:85]
	global_load_dwordx4 v[152:155], v[214:215], off
	global_load_dwordx4 v[160:163], v[214:215], off offset:1024
	global_load_dwordx4 v[164:167], v[214:215], off offset:2048
	global_load_dwordx4 v[168:171], v[214:215], off offset:3072
	global_load_dwordx4 v[172:175], v[216:217], off
	global_load_dwordx4 v[176:179], v[216:217], off offset:1024
	global_load_dwordx4 v[180:183], v[216:217], off offset:2048
	global_load_dwordx4 v[184:187], v[216:217], off offset:3072
	v_xor_b32_e32 v237, 16, v194
	v_xor_b32_e32 v238, 32, v194
	v_lshlrev_b32_e32 v237, 2, v237
	v_lshlrev_b32_e32 v238, 2, v238
	v_lshl_or_b32 v210, s22, 8, v189
	v_lshlrev_b32_e32 v210, 1, v210
	v_mov_b32_e32 v211, 0
	v_mov_b64_e32 v[212:213], s[52:53]
	v_mov_b32_e32 v218, 0xbdd2d3e8
	v_mov_b32_e32 v219, 0xc0135761
	s_waitcnt vmcnt(0)
	v_pk_add_f32 v[152:153], v[152:153], v[154:155]
	v_pk_add_f32 v[160:161], v[160:161], v[162:163]
	v_pk_add_f32 v[164:165], v[164:165], v[166:167]
	v_pk_add_f32 v[168:169], v[168:169], v[170:171]
	v_pk_add_f32 v[172:173], v[172:173], v[174:175]
	v_pk_add_f32 v[176:177], v[176:177], v[178:179]
	v_pk_add_f32 v[180:181], v[180:181], v[182:183]
	v_pk_add_f32 v[184:185], v[184:185], v[186:187]
	v_add_f32_e32 v150, v152, v153
	v_add_f32_e32 v156, v160, v161
	v_add_f32_e32 v196, v164, v165
	v_add_f32_e32 v198, v168, v169
	v_add_f32_e32 v200, v172, v173
	v_add_f32_e32 v202, v176, v177
	v_add_f32_e32 v204, v180, v181
	v_add_f32_e32 v206, v184, v185
	ds_bpermute_b32 v151, v237, v150
	ds_bpermute_b32 v157, v237, v156
	ds_bpermute_b32 v197, v237, v196
	ds_bpermute_b32 v199, v237, v198
	ds_bpermute_b32 v201, v237, v200
	ds_bpermute_b32 v203, v237, v202
	ds_bpermute_b32 v205, v237, v204
	ds_bpermute_b32 v207, v237, v206
	s_waitcnt lgkmcnt(7)
	v_add_f32_e32 v150, v150, v151
	s_waitcnt lgkmcnt(6)
	v_add_f32_e32 v156, v156, v157
	s_waitcnt lgkmcnt(5)
	v_add_f32_e32 v196, v196, v197
	s_waitcnt lgkmcnt(4)
	v_add_f32_e32 v198, v198, v199
	s_waitcnt lgkmcnt(3)
	v_add_f32_e32 v200, v200, v201
	s_waitcnt lgkmcnt(2)
	v_add_f32_e32 v202, v202, v203
	s_waitcnt lgkmcnt(1)
	v_add_f32_e32 v204, v204, v205
	s_waitcnt lgkmcnt(0)
	v_add_f32_e32 v206, v206, v207
	ds_bpermute_b32 v151, v238, v150
	ds_bpermute_b32 v157, v238, v156
	ds_bpermute_b32 v197, v238, v196
	ds_bpermute_b32 v199, v238, v198
	ds_bpermute_b32 v201, v238, v200
	ds_bpermute_b32 v203, v238, v202
	ds_bpermute_b32 v205, v238, v204
	ds_bpermute_b32 v207, v238, v206
	s_waitcnt lgkmcnt(7)
	v_add_f32_e32 v150, v150, v151
	s_waitcnt lgkmcnt(6)
	v_add_f32_e32 v156, v156, v157
	s_waitcnt lgkmcnt(5)
	v_add_f32_e32 v196, v196, v197
	s_waitcnt lgkmcnt(4)
	v_add_f32_e32 v198, v198, v199
	s_waitcnt lgkmcnt(3)
	v_add_f32_e32 v200, v200, v201
	s_waitcnt lgkmcnt(2)
	v_add_f32_e32 v202, v202, v203
	s_waitcnt lgkmcnt(1)
	v_add_f32_e32 v204, v204, v205
	s_waitcnt lgkmcnt(0)
	v_add_f32_e32 v206, v206, v207
	v_fmamk_f32 v150, v150, 0x3a800000, v195
	v_fmamk_f32 v156, v156, 0x3a800000, v195
	v_fmamk_f32 v196, v196, 0x3a800000, v195
	v_fmamk_f32 v198, v198, 0x3a800000, v195
	v_fmamk_f32 v200, v200, 0x3a800000, v195
	v_fmamk_f32 v202, v202, 0x3a800000, v195
	v_fmamk_f32 v204, v204, 0x3a800000, v195
	v_fmamk_f32 v206, v206, 0x3a800000, v195
	v_rsq_f32_e32 v128, v150
	v_rsq_f32_e32 v158, v156
	v_rsq_f32_e32 v224, v196
	v_rsq_f32_e32 v226, v198
	v_rsq_f32_e32 v228, v200
	v_rsq_f32_e32 v230, v202
	v_rsq_f32_e32 v232, v204
	v_rsq_f32_e32 v234, v206
	s_cmp_gt_i32 s22, 3
	s_cbranch_scc1 .Lepiz_plain_p3
	s_cmp_gt_i32 s22, 1
	s_cbranch_scc1 .Lepiz_va_p3
	v_pk_mul_f32 v[124:125], v[124:125], v[128:129] op_sel_hi:[1,0]
	v_pk_mul_f32 v[126:127], v[126:127], v[128:129] op_sel_hi:[1,0]
	v_pk_mul_f32 v[120:121], v[120:121], v[128:129] op_sel_hi:[1,0]
	v_pk_mul_f32 v[122:123], v[122:123], v[128:129] op_sel_hi:[1,0]
	v_pk_mul_f32 v[116:117], v[116:117], v[128:129] op_sel_hi:[1,0]
	v_pk_mul_f32 v[118:119], v[118:119], v[128:129] op_sel_hi:[1,0]
	v_pk_mul_f32 v[112:113], v[112:113], v[128:129] op_sel_hi:[1,0]
	v_pk_mul_f32 v[114:115], v[114:115], v[128:129] op_sel_hi:[1,0]
	v_pk_mul_f32 v[152:153], v[124:125], v[124:125]
	v_pk_mul_f32 v[160:161], v[126:127], v[126:127]
	v_pk_mul_f32 v[164:165], v[120:121], v[120:121]
	v_pk_mul_f32 v[168:169], v[122:123], v[122:123]
	v_pk_mul_f32 v[172:173], v[116:117], v[116:117]
	v_pk_mul_f32 v[176:177], v[118:119], v[118:119]
	v_pk_mul_f32 v[180:181], v[112:113], v[112:113]
	v_pk_mul_f32 v[184:185], v[114:115], v[114:115]
	v_pk_fma_f32 v[152:153], v[152:153], v[218:219], v[218:219] op_sel:[0,0,1] op_sel_hi:[1,0,1]
	v_pk_fma_f32 v[160:161], v[160:161], v[218:219], v[218:219] op_sel:[0,0,1] op_sel_hi:[1,0,1]
	v_pk_fma_f32 v[164:165], v[164:165], v[218:219], v[218:219] op_sel:[0,0,1] op_sel_hi:[1,0,1]
	v_pk_fma_f32 v[168:169], v[168:169], v[218:219], v[218:219] op_sel:[0,0,1] op_sel_hi:[1,0,1]
	v_pk_fma_f32 v[172:173], v[172:173], v[218:219], v[218:219] op_sel:[0,0,1] op_sel_hi:[1,0,1]
	v_pk_fma_f32 v[176:177], v[176:177], v[218:219], v[218:219] op_sel:[0,0,1] op_sel_hi:[1,0,1]
	v_pk_fma_f32 v[180:181], v[180:181], v[218:219], v[218:219] op_sel:[0,0,1] op_sel_hi:[1,0,1]
	v_pk_fma_f32 v[184:185], v[184:185], v[218:219], v[218:219] op_sel:[0,0,1] op_sel_hi:[1,0,1]
; __device__ __forceinline__ unsigned cvt_pk_bf16(float lo, float hi) { unsigned r; asm volatile("v_cvt_pk_bf16_f32 %0, %1, %2" : "=v"(r) : "v"(lo), "v"(hi)); return r; }
; __device__ __forceinline__ float fast_rcp(float x) { return __builtin_amdgcn_rcpf(x); }
; __device__ __forceinline__ unsigned cvt_pk_bf16(float lo, float hi) { const f32x2 v = {lo, hi}; const bf16x2_t b = __builtin_convertvector(v, bf16x2_t); return __builtin_bit_cast(unsigned, b); }
;     __device__ __forceinline__ void operator()(const f32x4 (&acc)[2][2][4][2], const Unit& u, int wr, int wc, int fr, int fq) const {
;     ...
;                 const int r = row0 + ai * HALF + m * 16; const float rs = rsv[ai][m];
;                 float s1 = 0.f, s2 = 0.f;
; #pragma unroll
;                 for (int bj = 0; bj < 2; ++bj) {
;                     f32x4 a = acc[ai][bj][m][0] * rs, b = acc[ai][bj][m][1] * rs;
;                     if (u.pn < gelu_tiles) {
; #pragma unroll
;                         for (int j = 0; j < 4; ++j) { const float ua = 1.5957691216057308f * a[j] * (1.0f + 0.044715f * a[j] * a[j]), ub = 1.5957691216057308f * b[j] * (1.0f + 0.044715f * b[j] * b[j]);
;                             a[j] = a[j] * fast_rcp(1.0f + __expf(-ua)); b[j] = b[j] * fast_rcp(1.0f + __expf(-ub)); }
;                     }
;                     if (va_tile) {
;                         s1 += ((a[0] + a[1]) + (a[2] + a[3])) + ((b[0] + b[1]) + (b[2] + b[3]));
;                         s2 += ((a[0] * a[0] + a[1] * a[1]) + (a[2] * a[2] + a[3] * a[3])) + ((b[0] * b[0] + b[1] * b[1]) + (b[2] * b[2] + b[3] * b[3]));
;                     }
;                     u32x4 w; w.x = cvt_pk_bf16(a[0], a[1]); w.y = cvt_pk_bf16(a[2], a[3]); w.z = cvt_pk_bf16(b[0], b[1]); w.w = cvt_pk_bf16(b[2], b[3]);
;                     *(u32x4*)(O + (size_t)r * ldo + col0 + bj * HALF) = w;
	v_pk_mul_f32 v[152:153], v[152:153], v[124:125]
	v_pk_mul_f32 v[160:161], v[160:161], v[126:127]
	v_pk_mul_f32 v[164:165], v[164:165], v[120:121]
	v_pk_mul_f32 v[168:169], v[168:169], v[122:123]
	v_pk_mul_f32 v[172:173], v[172:173], v[116:117]
	v_pk_mul_f32 v[176:177], v[176:177], v[118:119]
	v_pk_mul_f32 v[180:181], v[180:181], v[112:113]
	v_pk_mul_f32 v[184:185], v[184:185], v[114:115]
	v_exp_f32_e32 v152, v152
	v_exp_f32_e32 v153, v153
	v_exp_f32_e32 v160, v160
	v_exp_f32_e32 v161, v161
	v_exp_f32_e32 v164, v164
	v_exp_f32_e32 v165, v165
	v_exp_f32_e32 v168, v168
	v_exp_f32_e32 v169, v169
	v_exp_f32_e32 v172, v172
	v_exp_f32_e32 v173, v173
	v_exp_f32_e32 v176, v176
	v_exp_f32_e32 v177, v177
	v_exp_f32_e32 v180, v180
	v_exp_f32_e32 v181, v181
	v_exp_f32_e32 v184, v184
	v_exp_f32_e32 v185, v185
	v_pk_add_f32 v[152:153], v[152:153], 1.0 op_sel_hi:[1,0]
	v_pk_add_f32 v[160:161], v[160:161], 1.0 op_sel_hi:[1,0]
	v_pk_add_f32 v[164:165], v[164:165], 1.0 op_sel_hi:[1,0]
	v_pk_add_f32 v[168:169], v[168:169], 1.0 op_sel_hi:[1,0]
	v_pk_add_f32 v[172:173], v[172:173], 1.0 op_sel_hi:[1,0]
	v_pk_add_f32 v[176:177], v[176:177], 1.0 op_sel_hi:[1,0]
	v_pk_add_f32 v[180:181], v[180:181], 1.0 op_sel_hi:[1,0]
	v_pk_add_f32 v[184:185], v[184:185], 1.0 op_sel_hi:[1,0]
	v_rcp_f32_e32 v152, v152
	v_rcp_f32_e32 v153, v153
	v_rcp_f32_e32 v160, v160
	v_rcp_f32_e32 v161, v161
	v_rcp_f32_e32 v164, v164
	v_rcp_f32_e32 v165, v165
	v_rcp_f32_e32 v168, v168
	v_rcp_f32_e32 v169, v169
	v_rcp_f32_e32 v172, v172
	v_rcp_f32_e32 v173, v173
	v_rcp_f32_e32 v176, v176
	v_rcp_f32_e32 v177, v177
	v_rcp_f32_e32 v180, v180
	v_rcp_f32_e32 v181, v181
	v_rcp_f32_e32 v184, v184
	v_rcp_f32_e32 v185, v185
	v_pk_mul_f32 v[124:125], v[124:125], v[152:153]
	v_pk_mul_f32 v[126:127], v[126:127], v[160:161]
	v_pk_mul_f32 v[120:121], v[120:121], v[164:165]
	v_pk_mul_f32 v[122:123], v[122:123], v[168:169]
	v_pk_mul_f32 v[116:117], v[116:117], v[172:173]
	v_pk_mul_f32 v[118:119], v[118:119], v[176:177]
	v_pk_mul_f32 v[112:113], v[112:113], v[180:181]
	v_pk_mul_f32 v[114:115], v[114:115], v[184:185]
	v_cvt_pk_bf16_f32 v124, v124, v125
	v_cvt_pk_bf16_f32 v125, v126, v127
	v_cvt_pk_bf16_f32 v126, v120, v121
	v_cvt_pk_bf16_f32 v127, v122, v123
	v_mad_i64_i32 v[216:217], s[90:91], v208, s80, v[212:213]
	v_lshl_add_u64 v[216:217], v[216:217], 0, v[210:211]
	global_store_dwordx4 v[216:217], v[124:127], off
	v_cvt_pk_bf16_f32 v116, v116, v117
	v_cvt_pk_bf16_f32 v117, v118, v119
	v_cvt_pk_bf16_f32 v118, v112, v113
	v_cvt_pk_bf16_f32 v119, v114, v115
	global_store_dwordx4 v[216:217], v[116:119], off offset:256
	v_pk_mul_f32 v[108:109], v[108:109], v[158:159] op_sel_hi:[1,0]
	v_pk_mul_f32 v[110:111], v[110:111], v[158:159] op_sel_hi:[1,0]
	v_pk_mul_f32 v[104:105], v[104:105], v[158:159] op_sel_hi:[1,0]
	v_pk_mul_f32 v[106:107], v[106:107], v[158:159] op_sel_hi:[1,0]
	v_pk_mul_f32 v[100:101], v[100:101], v[158:159] op_sel_hi:[1,0]
	v_pk_mul_f32 v[102:103], v[102:103], v[158:159] op_sel_hi:[1,0]
	v_pk_mul_f32 v[96:97], v[96:97], v[158:159] op_sel_hi:[1,0]
	v_pk_mul_f32 v[98:99], v[98:99], v[158:159] op_sel_hi:[1,0]
	v_pk_mul_f32 v[152:153], v[108:109], v[108:109]
	v_pk_mul_f32 v[160:161], v[110:111], v[110:111]
	v_pk_mul_f32 v[164:165], v[104:105], v[104:105]
	v_pk_mul_f32 v[168:169], v[106:107], v[106:107]
	v_pk_mul_f32 v[172:173], v[100:101], v[100:101]
	v_pk_mul_f32 v[176:177], v[102:103], v[102:103]
	v_pk_mul_f32 v[180:181], v[96:97], v[96:97]
	v_pk_mul_f32 v[184:185], v[98:99], v[98:99]
	v_pk_fma_f32 v[152:153], v[152:153], v[218:219], v[218:219] op_sel:[0,0,1] op_sel_hi:[1,0,1]
	v_pk_fma_f32 v[160:161], v[160:161], v[218:219], v[218:219] op_sel:[0,0,1] op_sel_hi:[1,0,1]
	v_pk_fma_f32 v[164:165], v[164:165], v[218:219], v[218:219] op_sel:[0,0,1] op_sel_hi:[1,0,1]
	v_pk_fma_f32 v[168:169], v[168:169], v[218:219], v[218:219] op_sel:[0,0,1] op_sel_hi:[1,0,1]
	v_pk_fma_f32 v[172:173], v[172:173], v[218:219], v[218:219] op_sel:[0,0,1] op_sel_hi:[1,0,1]
	v_pk_fma_f32 v[176:177], v[176:177], v[218:219], v[218:219] op_sel:[0,0,1] op_sel_hi:[1,0,1]
	v_pk_fma_f32 v[180:181], v[180:181], v[218:219], v[218:219] op_sel:[0,0,1] op_sel_hi:[1,0,1]
	v_pk_fma_f32 v[184:185], v[184:185], v[218:219], v[218:219] op_sel:[0,0,1] op_sel_hi:[1,0,1]
	v_pk_mul_f32 v[152:153], v[152:153], v[108:109]
	v_pk_mul_f32 v[160:161], v[160:161], v[110:111]
	v_pk_mul_f32 v[164:165], v[164:165], v[104:105]
	v_pk_mul_f32 v[168:169], v[168:169], v[106:107]
	v_pk_mul_f32 v[172:173], v[172:173], v[100:101]
	v_pk_mul_f32 v[176:177], v[176:177], v[102:103]
	v_pk_mul_f32 v[180:181], v[180:181], v[96:97]
	v_pk_mul_f32 v[184:185], v[184:185], v[98:99]
	v_exp_f32_e32 v152, v152
	v_exp_f32_e32 v153, v153
	v_exp_f32_e32 v160, v160
	v_exp_f32_e32 v161, v161
	v_exp_f32_e32 v164, v164
	v_exp_f32_e32 v165, v165
	v_exp_f32_e32 v168, v168
	v_exp_f32_e32 v169, v169
	v_exp_f32_e32 v172, v172
	v_exp_f32_e32 v173, v173
	v_exp_f32_e32 v176, v176
	v_exp_f32_e32 v177, v177
	v_exp_f32_e32 v180, v180
	v_exp_f32_e32 v181, v181
	v_exp_f32_e32 v184, v184
	v_exp_f32_e32 v185, v185
	v_pk_add_f32 v[152:153], v[152:153], 1.0 op_sel_hi:[1,0]
	v_pk_add_f32 v[160:161], v[160:161], 1.0 op_sel_hi:[1,0]
	v_pk_add_f32 v[164:165], v[164:165], 1.0 op_sel_hi:[1,0]
	v_pk_add_f32 v[168:169], v[168:169], 1.0 op_sel_hi:[1,0]
	v_pk_add_f32 v[172:173], v[172:173], 1.0 op_sel_hi:[1,0]
	v_pk_add_f32 v[176:177], v[176:177], 1.0 op_sel_hi:[1,0]
	v_pk_add_f32 v[180:181], v[180:181], 1.0 op_sel_hi:[1,0]
	v_pk_add_f32 v[184:185], v[184:185], 1.0 op_sel_hi:[1,0]
	v_rcp_f32_e32 v152, v152
	v_rcp_f32_e32 v153, v153
	v_rcp_f32_e32 v160, v160
	v_rcp_f32_e32 v161, v161
	v_rcp_f32_e32 v164, v164
; __device__ __forceinline__ unsigned cvt_pk_bf16(float lo, float hi) { unsigned r; asm volatile("v_cvt_pk_bf16_f32 %0, %1, %2" : "=v"(r) : "v"(lo), "v"(hi)); return r; }
; __device__ __forceinline__ float fast_rcp(float x) { return __builtin_amdgcn_rcpf(x); }
; __device__ __forceinline__ unsigned cvt_pk_bf16(float lo, float hi) { const f32x2 v = {lo, hi}; const bf16x2_t b = __builtin_convertvector(v, bf16x2_t); return __builtin_bit_cast(unsigned, b); }
;     __device__ __forceinline__ void operator()(const f32x4 (&acc)[2][2][4][2], const Unit& u, int wr, int wc, int fr, int fq) const {
;     ...
;                 const int r = row0 + ai * HALF + m * 16; const float rs = rsv[ai][m];
;                 float s1 = 0.f, s2 = 0.f;
; #pragma unroll
;                 for (int bj = 0; bj < 2; ++bj) {
;                     f32x4 a = acc[ai][bj][m][0] * rs, b = acc[ai][bj][m][1] * rs;
;                     if (u.pn < gelu_tiles) {
; #pragma unroll
;                         for (int j = 0; j < 4; ++j) { const float ua = 1.5957691216057308f * a[j] * (1.0f + 0.044715f * a[j] * a[j]), ub = 1.5957691216057308f * b[j] * (1.0f + 0.044715f * b[j] * b[j]);
;                             a[j] = a[j] * fast_rcp(1.0f + __expf(-ua)); b[j] = b[j] * fast_rcp(1.0f + __expf(-ub)); }
;                     }
;                     if (va_tile) {
;                         s1 += ((a[0] + a[1]) + (a[2] + a[3])) + ((b[0] + b[1]) + (b[2] + b[3]));
;                         s2 += ((a[0] * a[0] + a[1] * a[1]) + (a[2] * a[2] + a[3] * a[3])) + ((b[0] * b[0] + b[1] * b[1]) + (b[2] * b[2] + b[3] * b[3]));
;                     }
;                     u32x4 w; w.x = cvt_pk_bf16(a[0], a[1]); w.y = cvt_pk_bf16(a[2], a[3]); w.z = cvt_pk_bf16(b[0], b[1]); w.w = cvt_pk_bf16(b[2], b[3]);
;                     *(u32x4*)(O + (size_t)r * ldo + col0 + bj * HALF) = w;
	v_rcp_f32_e32 v165, v165
	v_rcp_f32_e32 v168, v168
	v_rcp_f32_e32 v169, v169
	v_rcp_f32_e32 v172, v172
	v_rcp_f32_e32 v173, v173
	v_rcp_f32_e32 v176, v176
	v_rcp_f32_e32 v177, v177
	v_rcp_f32_e32 v180, v180
	v_rcp_f32_e32 v181, v181
	v_rcp_f32_e32 v184, v184
	v_rcp_f32_e32 v185, v185
	v_pk_mul_f32 v[108:109], v[108:109], v[152:153]
	v_pk_mul_f32 v[110:111], v[110:111], v[160:161]
	v_pk_mul_f32 v[104:105], v[104:105], v[164:165]
	v_pk_mul_f32 v[106:107], v[106:107], v[168:169]
	v_pk_mul_f32 v[100:101], v[100:101], v[172:173]
	v_pk_mul_f32 v[102:103], v[102:103], v[176:177]
	v_pk_mul_f32 v[96:97], v[96:97], v[180:181]
	v_pk_mul_f32 v[98:99], v[98:99], v[184:185]
	v_cvt_pk_bf16_f32 v108, v108, v109
	v_cvt_pk_bf16_f32 v109, v110, v111
	v_cvt_pk_bf16_f32 v110, v104, v105
	v_cvt_pk_bf16_f32 v111, v106, v107
	v_mad_i64_i32 v[216:217], s[90:91], v225, s80, v[212:213]
	v_lshl_add_u64 v[216:217], v[216:217], 0, v[210:211]
	global_store_dwordx4 v[216:217], v[108:111], off
	v_cvt_pk_bf16_f32 v100, v100, v101
	v_cvt_pk_bf16_f32 v101, v102, v103
	v_cvt_pk_bf16_f32 v102, v96, v97
	v_cvt_pk_bf16_f32 v103, v98, v99
	global_store_dwordx4 v[216:217], v[100:103], off offset:256
	v_pk_mul_f32 v[92:93], v[92:93], v[224:225] op_sel_hi:[1,0]
	v_pk_mul_f32 v[94:95], v[94:95], v[224:225] op_sel_hi:[1,0]
	v_pk_mul_f32 v[88:89], v[88:89], v[224:225] op_sel_hi:[1,0]
	v_pk_mul_f32 v[90:91], v[90:91], v[224:225] op_sel_hi:[1,0]
	v_pk_mul_f32 v[84:85], v[84:85], v[224:225] op_sel_hi:[1,0]
	v_pk_mul_f32 v[86:87], v[86:87], v[224:225] op_sel_hi:[1,0]
	v_pk_mul_f32 v[80:81], v[80:81], v[224:225] op_sel_hi:[1,0]
	v_pk_mul_f32 v[82:83], v[82:83], v[224:225] op_sel_hi:[1,0]
	v_pk_mul_f32 v[152:153], v[92:93], v[92:93]
	v_pk_mul_f32 v[160:161], v[94:95], v[94:95]
	v_pk_mul_f32 v[164:165], v[88:89], v[88:89]
	v_pk_mul_f32 v[168:169], v[90:91], v[90:91]
	v_pk_mul_f32 v[172:173], v[84:85], v[84:85]
	v_pk_mul_f32 v[176:177], v[86:87], v[86:87]
	v_pk_mul_f32 v[180:181], v[80:81], v[80:81]
	v_pk_mul_f32 v[184:185], v[82:83], v[82:83]
	v_pk_fma_f32 v[152:153], v[152:153], v[218:219], v[218:219] op_sel:[0,0,1] op_sel_hi:[1,0,1]
	v_pk_fma_f32 v[160:161], v[160:161], v[218:219], v[218:219] op_sel:[0,0,1] op_sel_hi:[1,0,1]
	v_pk_fma_f32 v[164:165], v[164:165], v[218:219], v[218:219] op_sel:[0,0,1] op_sel_hi:[1,0,1]
	v_pk_fma_f32 v[168:169], v[168:169], v[218:219], v[218:219] op_sel:[0,0,1] op_sel_hi:[1,0,1]
	v_pk_fma_f32 v[172:173], v[172:173], v[218:219], v[218:219] op_sel:[0,0,1] op_sel_hi:[1,0,1]
	v_pk_fma_f32 v[176:177], v[176:177], v[218:219], v[218:219] op_sel:[0,0,1] op_sel_hi:[1,0,1]
	v_pk_fma_f32 v[180:181], v[180:181], v[218:219], v[218:219] op_sel:[0,0,1] op_sel_hi:[1,0,1]
	v_pk_fma_f32 v[184:185], v[184:185], v[218:219], v[218:219] op_sel:[0,0,1] op_sel_hi:[1,0,1]
	v_pk_mul_f32 v[152:153], v[152:153], v[92:93]
	v_pk_mul_f32 v[160:161], v[160:161], v[94:95]
	v_pk_mul_f32 v[164:165], v[164:165], v[88:89]
	v_pk_mul_f32 v[168:169], v[168:169], v[90:91]
	v_pk_mul_f32 v[172:173], v[172:173], v[84:85]
	v_pk_mul_f32 v[176:177], v[176:177], v[86:87]
	v_pk_mul_f32 v[180:181], v[180:181], v[80:81]
	v_pk_mul_f32 v[184:185], v[184:185], v[82:83]
	v_exp_f32_e32 v152, v152
	v_exp_f32_e32 v153, v153
	v_exp_f32_e32 v160, v160
	v_exp_f32_e32 v161, v161
	v_exp_f32_e32 v164, v164
	v_exp_f32_e32 v165, v165
	v_exp_f32_e32 v168, v168
	v_exp_f32_e32 v169, v169
	v_exp_f32_e32 v172, v172
	v_exp_f32_e32 v173, v173
	v_exp_f32_e32 v176, v176
	v_exp_f32_e32 v177, v177
	v_exp_f32_e32 v180, v180
	v_exp_f32_e32 v181, v181
	v_exp_f32_e32 v184, v184
	v_exp_f32_e32 v185, v185
	v_pk_add_f32 v[152:153], v[152:153], 1.0 op_sel_hi:[1,0]
	v_pk_add_f32 v[160:161], v[160:161], 1.0 op_sel_hi:[1,0]
	v_pk_add_f32 v[164:165], v[164:165], 1.0 op_sel_hi:[1,0]
	v_pk_add_f32 v[168:169], v[168:169], 1.0 op_sel_hi:[1,0]
	v_pk_add_f32 v[172:173], v[172:173], 1.0 op_sel_hi:[1,0]
	v_pk_add_f32 v[176:177], v[176:177], 1.0 op_sel_hi:[1,0]
	v_pk_add_f32 v[180:181], v[180:181], 1.0 op_sel_hi:[1,0]
	v_pk_add_f32 v[184:185], v[184:185], 1.0 op_sel_hi:[1,0]
	v_rcp_f32_e32 v152, v152
	v_rcp_f32_e32 v153, v153
	v_rcp_f32_e32 v160, v160
	v_rcp_f32_e32 v161, v161
	v_rcp_f32_e32 v164, v164
	v_rcp_f32_e32 v165, v165
	v_rcp_f32_e32 v168, v168
	v_rcp_f32_e32 v169, v169
	v_rcp_f32_e32 v172, v172
	v_rcp_f32_e32 v173, v173
	v_rcp_f32_e32 v176, v176
	v_rcp_f32_e32 v177, v177
	v_rcp_f32_e32 v180, v180
	v_rcp_f32_e32 v181, v181
	v_rcp_f32_e32 v184, v184
	v_rcp_f32_e32 v185, v185
	v_pk_mul_f32 v[92:93], v[92:93], v[152:153]
	v_pk_mul_f32 v[94:95], v[94:95], v[160:161]
	v_pk_mul_f32 v[88:89], v[88:89], v[164:165]
	v_pk_mul_f32 v[90:91], v[90:91], v[168:169]
	v_pk_mul_f32 v[84:85], v[84:85], v[172:173]
	v_pk_mul_f32 v[86:87], v[86:87], v[176:177]
	v_pk_mul_f32 v[80:81], v[80:81], v[180:181]
	v_pk_mul_f32 v[82:83], v[82:83], v[184:185]
	v_cvt_pk_bf16_f32 v92, v92, v93
	v_cvt_pk_bf16_f32 v93, v94, v95
	v_cvt_pk_bf16_f32 v94, v88, v89
	v_cvt_pk_bf16_f32 v95, v90, v91
	v_mad_i64_i32 v[216:217], s[90:91], v227, s80, v[212:213]
	v_lshl_add_u64 v[216:217], v[216:217], 0, v[210:211]
	global_store_dwordx4 v[216:217], v[92:95], off
	v_cvt_pk_bf16_f32 v84, v84, v85
	v_cvt_pk_bf16_f32 v85, v86, v87
	v_cvt_pk_bf16_f32 v86, v80, v81
	v_cvt_pk_bf16_f32 v87, v82, v83
	global_store_dwordx4 v[216:217], v[84:87], off offset:256
	v_pk_mul_f32 v[76:77], v[76:77], v[226:227] op_sel_hi:[1,0]
	v_pk_mul_f32 v[78:79], v[78:79], v[226:227] op_sel_hi:[1,0]
	v_pk_mul_f32 v[72:73], v[72:73], v[226:227] op_sel_hi:[1,0]
	v_pk_mul_f32 v[74:75], v[74:75], v[226:227] op_sel_hi:[1,0]
	v_pk_mul_f32 v[68:69], v[68:69], v[226:227] op_sel_hi:[1,0]
	v_pk_mul_f32 v[70:71], v[70:71], v[226:227] op_sel_hi:[1,0]
; __device__ __forceinline__ unsigned cvt_pk_bf16(float lo, float hi) { unsigned r; asm volatile("v_cvt_pk_bf16_f32 %0, %1, %2" : "=v"(r) : "v"(lo), "v"(hi)); return r; }
; __device__ __forceinline__ float fast_rcp(float x) { return __builtin_amdgcn_rcpf(x); }
; __device__ __forceinline__ unsigned cvt_pk_bf16(float lo, float hi) { const f32x2 v = {lo, hi}; const bf16x2_t b = __builtin_convertvector(v, bf16x2_t); return __builtin_bit_cast(unsigned, b); }
;     __device__ __forceinline__ void operator()(const f32x4 (&acc)[2][2][4][2], const Unit& u, int wr, int wc, int fr, int fq) const {
;     ...
;                 const int r = row0 + ai * HALF + m * 16; const float rs = rsv[ai][m];
;                 float s1 = 0.f, s2 = 0.f;
; #pragma unroll
;                 for (int bj = 0; bj < 2; ++bj) {
;                     f32x4 a = acc[ai][bj][m][0] * rs, b = acc[ai][bj][m][1] * rs;
;                     if (u.pn < gelu_tiles) {
; #pragma unroll
;                         for (int j = 0; j < 4; ++j) { const float ua = 1.5957691216057308f * a[j] * (1.0f + 0.044715f * a[j] * a[j]), ub = 1.5957691216057308f * b[j] * (1.0f + 0.044715f * b[j] * b[j]);
;                             a[j] = a[j] * fast_rcp(1.0f + __expf(-ua)); b[j] = b[j] * fast_rcp(1.0f + __expf(-ub)); }
;                     }
;                     if (va_tile) {
;                         s1 += ((a[0] + a[1]) + (a[2] + a[3])) + ((b[0] + b[1]) + (b[2] + b[3]));
;                         s2 += ((a[0] * a[0] + a[1] * a[1]) + (a[2] * a[2] + a[3] * a[3])) + ((b[0] * b[0] + b[1] * b[1]) + (b[2] * b[2] + b[3] * b[3]));
;                     }
;                     u32x4 w; w.x = cvt_pk_bf16(a[0], a[1]); w.y = cvt_pk_bf16(a[2], a[3]); w.z = cvt_pk_bf16(b[0], b[1]); w.w = cvt_pk_bf16(b[2], b[3]);
;                     *(u32x4*)(O + (size_t)r * ldo + col0 + bj * HALF) = w;
	v_pk_mul_f32 v[64:65], v[64:65], v[226:227] op_sel_hi:[1,0]
	v_pk_mul_f32 v[66:67], v[66:67], v[226:227] op_sel_hi:[1,0]
	v_pk_mul_f32 v[152:153], v[76:77], v[76:77]
	v_pk_mul_f32 v[160:161], v[78:79], v[78:79]
	v_pk_mul_f32 v[164:165], v[72:73], v[72:73]
	v_pk_mul_f32 v[168:169], v[74:75], v[74:75]
	v_pk_mul_f32 v[172:173], v[68:69], v[68:69]
	v_pk_mul_f32 v[176:177], v[70:71], v[70:71]
	v_pk_mul_f32 v[180:181], v[64:65], v[64:65]
	v_pk_mul_f32 v[184:185], v[66:67], v[66:67]
	v_pk_fma_f32 v[152:153], v[152:153], v[218:219], v[218:219] op_sel:[0,0,1] op_sel_hi:[1,0,1]
	v_pk_fma_f32 v[160:161], v[160:161], v[218:219], v[218:219] op_sel:[0,0,1] op_sel_hi:[1,0,1]
	v_pk_fma_f32 v[164:165], v[164:165], v[218:219], v[218:219] op_sel:[0,0,1] op_sel_hi:[1,0,1]
	v_pk_fma_f32 v[168:169], v[168:169], v[218:219], v[218:219] op_sel:[0,0,1] op_sel_hi:[1,0,1]
	v_pk_fma_f32 v[172:173], v[172:173], v[218:219], v[218:219] op_sel:[0,0,1] op_sel_hi:[1,0,1]
	v_pk_fma_f32 v[176:177], v[176:177], v[218:219], v[218:219] op_sel:[0,0,1] op_sel_hi:[1,0,1]
	v_pk_fma_f32 v[180:181], v[180:181], v[218:219], v[218:219] op_sel:[0,0,1] op_sel_hi:[1,0,1]
	v_pk_fma_f32 v[184:185], v[184:185], v[218:219], v[218:219] op_sel:[0,0,1] op_sel_hi:[1,0,1]
	v_pk_mul_f32 v[152:153], v[152:153], v[76:77]
	v_pk_mul_f32 v[160:161], v[160:161], v[78:79]
	v_pk_mul_f32 v[164:165], v[164:165], v[72:73]
	v_pk_mul_f32 v[168:169], v[168:169], v[74:75]
	v_pk_mul_f32 v[172:173], v[172:173], v[68:69]
	v_pk_mul_f32 v[176:177], v[176:177], v[70:71]
	v_pk_mul_f32 v[180:181], v[180:181], v[64:65]
	v_pk_mul_f32 v[184:185], v[184:185], v[66:67]
	v_exp_f32_e32 v152, v152
	v_exp_f32_e32 v153, v153
	v_exp_f32_e32 v160, v160
	v_exp_f32_e32 v161, v161
	v_exp_f32_e32 v164, v164
	v_exp_f32_e32 v165, v165
	v_exp_f32_e32 v168, v168
	v_exp_f32_e32 v169, v169
	v_exp_f32_e32 v172, v172
	v_exp_f32_e32 v173, v173
	v_exp_f32_e32 v176, v176
	v_exp_f32_e32 v177, v177
	v_exp_f32_e32 v180, v180
	v_exp_f32_e32 v181, v181
	v_exp_f32_e32 v184, v184
	v_exp_f32_e32 v185, v185
	v_pk_add_f32 v[152:153], v[152:153], 1.0 op_sel_hi:[1,0]
	v_pk_add_f32 v[160:161], v[160:161], 1.0 op_sel_hi:[1,0]
	v_pk_add_f32 v[164:165], v[164:165], 1.0 op_sel_hi:[1,0]
	v_pk_add_f32 v[168:169], v[168:169], 1.0 op_sel_hi:[1,0]
	v_pk_add_f32 v[172:173], v[172:173], 1.0 op_sel_hi:[1,0]
	v_pk_add_f32 v[176:177], v[176:177], 1.0 op_sel_hi:[1,0]
	v_pk_add_f32 v[180:181], v[180:181], 1.0 op_sel_hi:[1,0]
	v_pk_add_f32 v[184:185], v[184:185], 1.0 op_sel_hi:[1,0]
	v_rcp_f32_e32 v152, v152
	v_rcp_f32_e32 v153, v153
	v_rcp_f32_e32 v160, v160
	v_rcp_f32_e32 v161, v161
	v_rcp_f32_e32 v164, v164
	v_rcp_f32_e32 v165, v165
	v_rcp_f32_e32 v168, v168
	v_rcp_f32_e32 v169, v169
	v_rcp_f32_e32 v172, v172
	v_rcp_f32_e32 v173, v173
	v_rcp_f32_e32 v176, v176
	v_rcp_f32_e32 v177, v177
	v_rcp_f32_e32 v180, v180
	v_rcp_f32_e32 v181, v181
	v_rcp_f32_e32 v184, v184
	v_rcp_f32_e32 v185, v185
	v_pk_mul_f32 v[76:77], v[76:77], v[152:153]
	v_pk_mul_f32 v[78:79], v[78:79], v[160:161]
	v_pk_mul_f32 v[72:73], v[72:73], v[164:165]
	v_pk_mul_f32 v[74:75], v[74:75], v[168:169]
	v_pk_mul_f32 v[68:69], v[68:69], v[172:173]
	v_pk_mul_f32 v[70:71], v[70:71], v[176:177]
	v_pk_mul_f32 v[64:65], v[64:65], v[180:181]
	v_pk_mul_f32 v[66:67], v[66:67], v[184:185]
	v_cvt_pk_bf16_f32 v76, v76, v77
	v_cvt_pk_bf16_f32 v77, v78, v79
	v_cvt_pk_bf16_f32 v78, v72, v73
	v_cvt_pk_bf16_f32 v79, v74, v75
	v_mad_i64_i32 v[216:217], s[90:91], v229, s80, v[212:213]
	v_lshl_add_u64 v[216:217], v[216:217], 0, v[210:211]
	global_store_dwordx4 v[216:217], v[76:79], off
	v_cvt_pk_bf16_f32 v68, v68, v69
	v_cvt_pk_bf16_f32 v69, v70, v71
	v_cvt_pk_bf16_f32 v70, v64, v65
	v_cvt_pk_bf16_f32 v71, v66, v67
	global_store_dwordx4 v[216:217], v[68:71], off offset:256
	v_pk_mul_f32 v[60:61], v[60:61], v[228:229] op_sel_hi:[1,0]
	v_pk_mul_f32 v[62:63], v[62:63], v[228:229] op_sel_hi:[1,0]
	v_pk_mul_f32 v[56:57], v[56:57], v[228:229] op_sel_hi:[1,0]
	v_pk_mul_f32 v[58:59], v[58:59], v[228:229] op_sel_hi:[1,0]
	v_pk_mul_f32 v[52:53], v[52:53], v[228:229] op_sel_hi:[1,0]
	v_pk_mul_f32 v[54:55], v[54:55], v[228:229] op_sel_hi:[1,0]
	v_pk_mul_f32 v[48:49], v[48:49], v[228:229] op_sel_hi:[1,0]
	v_pk_mul_f32 v[50:51], v[50:51], v[228:229] op_sel_hi:[1,0]
	v_pk_mul_f32 v[152:153], v[60:61], v[60:61]
	v_pk_mul_f32 v[160:161], v[62:63], v[62:63]
	v_pk_mul_f32 v[164:165], v[56:57], v[56:57]
	v_pk_mul_f32 v[168:169], v[58:59], v[58:59]
	v_pk_mul_f32 v[172:173], v[52:53], v[52:53]
	v_pk_mul_f32 v[176:177], v[54:55], v[54:55]
	v_pk_mul_f32 v[180:181], v[48:49], v[48:49]
	v_pk_mul_f32 v[184:185], v[50:51], v[50:51]
	v_pk_fma_f32 v[152:153], v[152:153], v[218:219], v[218:219] op_sel:[0,0,1] op_sel_hi:[1,0,1]
	v_pk_fma_f32 v[160:161], v[160:161], v[218:219], v[218:219] op_sel:[0,0,1] op_sel_hi:[1,0,1]
	v_pk_fma_f32 v[164:165], v[164:165], v[218:219], v[218:219] op_sel:[0,0,1] op_sel_hi:[1,0,1]
	v_pk_fma_f32 v[168:169], v[168:169], v[218:219], v[218:219] op_sel:[0,0,1] op_sel_hi:[1,0,1]
	v_pk_fma_f32 v[172:173], v[172:173], v[218:219], v[218:219] op_sel:[0,0,1] op_sel_hi:[1,0,1]
	v_pk_fma_f32 v[176:177], v[176:177], v[218:219], v[218:219] op_sel:[0,0,1] op_sel_hi:[1,0,1]
	v_pk_fma_f32 v[180:181], v[180:181], v[218:219], v[218:219] op_sel:[0,0,1] op_sel_hi:[1,0,1]
	v_pk_fma_f32 v[184:185], v[184:185], v[218:219], v[218:219] op_sel:[0,0,1] op_sel_hi:[1,0,1]
	v_pk_mul_f32 v[152:153], v[152:153], v[60:61]
	v_pk_mul_f32 v[160:161], v[160:161], v[62:63]
	v_pk_mul_f32 v[164:165], v[164:165], v[56:57]
	v_pk_mul_f32 v[168:169], v[168:169], v[58:59]
	v_pk_mul_f32 v[172:173], v[172:173], v[52:53]
	v_pk_mul_f32 v[176:177], v[176:177], v[54:55]
; __device__ __forceinline__ unsigned cvt_pk_bf16(float lo, float hi) { unsigned r; asm volatile("v_cvt_pk_bf16_f32 %0, %1, %2" : "=v"(r) : "v"(lo), "v"(hi)); return r; }
; __device__ __forceinline__ float fast_rcp(float x) { return __builtin_amdgcn_rcpf(x); }
; __device__ __forceinline__ unsigned cvt_pk_bf16(float lo, float hi) { const f32x2 v = {lo, hi}; const bf16x2_t b = __builtin_convertvector(v, bf16x2_t); return __builtin_bit_cast(unsigned, b); }
;     __device__ __forceinline__ void operator()(const f32x4 (&acc)[2][2][4][2], const Unit& u, int wr, int wc, int fr, int fq) const {
;     ...
;                 const int r = row0 + ai * HALF + m * 16; const float rs = rsv[ai][m];
;                 float s1 = 0.f, s2 = 0.f;
; #pragma unroll
;                 for (int bj = 0; bj < 2; ++bj) {
;                     f32x4 a = acc[ai][bj][m][0] * rs, b = acc[ai][bj][m][1] * rs;
;                     if (u.pn < gelu_tiles) {
; #pragma unroll
;                         for (int j = 0; j < 4; ++j) { const float ua = 1.5957691216057308f * a[j] * (1.0f + 0.044715f * a[j] * a[j]), ub = 1.5957691216057308f * b[j] * (1.0f + 0.044715f * b[j] * b[j]);
;                             a[j] = a[j] * fast_rcp(1.0f + __expf(-ua)); b[j] = b[j] * fast_rcp(1.0f + __expf(-ub)); }
;                     }
;                     if (va_tile) {
;                         s1 += ((a[0] + a[1]) + (a[2] + a[3])) + ((b[0] + b[1]) + (b[2] + b[3]));
;                         s2 += ((a[0] * a[0] + a[1] * a[1]) + (a[2] * a[2] + a[3] * a[3])) + ((b[0] * b[0] + b[1] * b[1]) + (b[2] * b[2] + b[3] * b[3]));
;                     }
;                     u32x4 w; w.x = cvt_pk_bf16(a[0], a[1]); w.y = cvt_pk_bf16(a[2], a[3]); w.z = cvt_pk_bf16(b[0], b[1]); w.w = cvt_pk_bf16(b[2], b[3]);
;                     *(u32x4*)(O + (size_t)r * ldo + col0 + bj * HALF) = w;
	v_pk_mul_f32 v[180:181], v[180:181], v[48:49]
	v_pk_mul_f32 v[184:185], v[184:185], v[50:51]
	v_exp_f32_e32 v152, v152
	v_exp_f32_e32 v153, v153
	v_exp_f32_e32 v160, v160
	v_exp_f32_e32 v161, v161
	v_exp_f32_e32 v164, v164
	v_exp_f32_e32 v165, v165
	v_exp_f32_e32 v168, v168
	v_exp_f32_e32 v169, v169
	v_exp_f32_e32 v172, v172
	v_exp_f32_e32 v173, v173
	v_exp_f32_e32 v176, v176
	v_exp_f32_e32 v177, v177
	v_exp_f32_e32 v180, v180
	v_exp_f32_e32 v181, v181
	v_exp_f32_e32 v184, v184
	v_exp_f32_e32 v185, v185
	v_pk_add_f32 v[152:153], v[152:153], 1.0 op_sel_hi:[1,0]
	v_pk_add_f32 v[160:161], v[160:161], 1.0 op_sel_hi:[1,0]
	v_pk_add_f32 v[164:165], v[164:165], 1.0 op_sel_hi:[1,0]
	v_pk_add_f32 v[168:169], v[168:169], 1.0 op_sel_hi:[1,0]
	v_pk_add_f32 v[172:173], v[172:173], 1.0 op_sel_hi:[1,0]
	v_pk_add_f32 v[176:177], v[176:177], 1.0 op_sel_hi:[1,0]
	v_pk_add_f32 v[180:181], v[180:181], 1.0 op_sel_hi:[1,0]
	v_pk_add_f32 v[184:185], v[184:185], 1.0 op_sel_hi:[1,0]
	v_rcp_f32_e32 v152, v152
	v_rcp_f32_e32 v153, v153
	v_rcp_f32_e32 v160, v160
	v_rcp_f32_e32 v161, v161
	v_rcp_f32_e32 v164, v164
	v_rcp_f32_e32 v165, v165
	v_rcp_f32_e32 v168, v168
	v_rcp_f32_e32 v169, v169
	v_rcp_f32_e32 v172, v172
	v_rcp_f32_e32 v173, v173
	v_rcp_f32_e32 v176, v176
	v_rcp_f32_e32 v177, v177
	v_rcp_f32_e32 v180, v180
	v_rcp_f32_e32 v181, v181
	v_rcp_f32_e32 v184, v184
	v_rcp_f32_e32 v185, v185
	v_pk_mul_f32 v[60:61], v[60:61], v[152:153]
	v_pk_mul_f32 v[62:63], v[62:63], v[160:161]
	v_pk_mul_f32 v[56:57], v[56:57], v[164:165]
	v_pk_mul_f32 v[58:59], v[58:59], v[168:169]
	v_pk_mul_f32 v[52:53], v[52:53], v[172:173]
	v_pk_mul_f32 v[54:55], v[54:55], v[176:177]
	v_pk_mul_f32 v[48:49], v[48:49], v[180:181]
	v_pk_mul_f32 v[50:51], v[50:51], v[184:185]
	v_cvt_pk_bf16_f32 v60, v60, v61
	v_cvt_pk_bf16_f32 v61, v62, v63
	v_cvt_pk_bf16_f32 v62, v56, v57
	v_cvt_pk_bf16_f32 v63, v58, v59
	v_mad_i64_i32 v[216:217], s[90:91], v231, s80, v[212:213]
	v_lshl_add_u64 v[216:217], v[216:217], 0, v[210:211]
	global_store_dwordx4 v[216:217], v[60:63], off
	v_cvt_pk_bf16_f32 v52, v52, v53
	v_cvt_pk_bf16_f32 v53, v54, v55
	v_cvt_pk_bf16_f32 v54, v48, v49
	v_cvt_pk_bf16_f32 v55, v50, v51
	global_store_dwordx4 v[216:217], v[52:55], off offset:256
	v_pk_mul_f32 v[44:45], v[44:45], v[230:231] op_sel_hi:[1,0]
	v_pk_mul_f32 v[46:47], v[46:47], v[230:231] op_sel_hi:[1,0]
	v_pk_mul_f32 v[40:41], v[40:41], v[230:231] op_sel_hi:[1,0]
	v_pk_mul_f32 v[42:43], v[42:43], v[230:231] op_sel_hi:[1,0]
	v_pk_mul_f32 v[36:37], v[36:37], v[230:231] op_sel_hi:[1,0]
	v_pk_mul_f32 v[38:39], v[38:39], v[230:231] op_sel_hi:[1,0]
	v_pk_mul_f32 v[32:33], v[32:33], v[230:231] op_sel_hi:[1,0]
	v_pk_mul_f32 v[34:35], v[34:35], v[230:231] op_sel_hi:[1,0]
	v_pk_mul_f32 v[152:153], v[44:45], v[44:45]
	v_pk_mul_f32 v[160:161], v[46:47], v[46:47]
	v_pk_mul_f32 v[164:165], v[40:41], v[40:41]
	v_pk_mul_f32 v[168:169], v[42:43], v[42:43]
	v_pk_mul_f32 v[172:173], v[36:37], v[36:37]
	v_pk_mul_f32 v[176:177], v[38:39], v[38:39]
	v_pk_mul_f32 v[180:181], v[32:33], v[32:33]
	v_pk_mul_f32 v[184:185], v[34:35], v[34:35]
	v_pk_fma_f32 v[152:153], v[152:153], v[218:219], v[218:219] op_sel:[0,0,1] op_sel_hi:[1,0,1]
	v_pk_fma_f32 v[160:161], v[160:161], v[218:219], v[218:219] op_sel:[0,0,1] op_sel_hi:[1,0,1]
	v_pk_fma_f32 v[164:165], v[164:165], v[218:219], v[218:219] op_sel:[0,0,1] op_sel_hi:[1,0,1]
	v_pk_fma_f32 v[168:169], v[168:169], v[218:219], v[218:219] op_sel:[0,0,1] op_sel_hi:[1,0,1]
	v_pk_fma_f32 v[172:173], v[172:173], v[218:219], v[218:219] op_sel:[0,0,1] op_sel_hi:[1,0,1]
	v_pk_fma_f32 v[176:177], v[176:177], v[218:219], v[218:219] op_sel:[0,0,1] op_sel_hi:[1,0,1]
	v_pk_fma_f32 v[180:181], v[180:181], v[218:219], v[218:219] op_sel:[0,0,1] op_sel_hi:[1,0,1]
	v_pk_fma_f32 v[184:185], v[184:185], v[218:219], v[218:219] op_sel:[0,0,1] op_sel_hi:[1,0,1]
	v_pk_mul_f32 v[152:153], v[152:153], v[44:45]
	v_pk_mul_f32 v[160:161], v[160:161], v[46:47]
	v_pk_mul_f32 v[164:165], v[164:165], v[40:41]
	v_pk_mul_f32 v[168:169], v[168:169], v[42:43]
	v_pk_mul_f32 v[172:173], v[172:173], v[36:37]
	v_pk_mul_f32 v[176:177], v[176:177], v[38:39]
	v_pk_mul_f32 v[180:181], v[180:181], v[32:33]
	v_pk_mul_f32 v[184:185], v[184:185], v[34:35]
	v_exp_f32_e32 v152, v152
	v_exp_f32_e32 v153, v153
	v_exp_f32_e32 v160, v160
	v_exp_f32_e32 v161, v161
	v_exp_f32_e32 v164, v164
	v_exp_f32_e32 v165, v165
	v_exp_f32_e32 v168, v168
	v_exp_f32_e32 v169, v169
	v_exp_f32_e32 v172, v172
	v_exp_f32_e32 v173, v173
	v_exp_f32_e32 v176, v176
	v_exp_f32_e32 v177, v177
	v_exp_f32_e32 v180, v180
	v_exp_f32_e32 v181, v181
	v_exp_f32_e32 v184, v184
	v_exp_f32_e32 v185, v185
	v_pk_add_f32 v[152:153], v[152:153], 1.0 op_sel_hi:[1,0]
	v_pk_add_f32 v[160:161], v[160:161], 1.0 op_sel_hi:[1,0]
	v_pk_add_f32 v[164:165], v[164:165], 1.0 op_sel_hi:[1,0]
	v_pk_add_f32 v[168:169], v[168:169], 1.0 op_sel_hi:[1,0]
	v_pk_add_f32 v[172:173], v[172:173], 1.0 op_sel_hi:[1,0]
	v_pk_add_f32 v[176:177], v[176:177], 1.0 op_sel_hi:[1,0]
	v_pk_add_f32 v[180:181], v[180:181], 1.0 op_sel_hi:[1,0]
	v_pk_add_f32 v[184:185], v[184:185], 1.0 op_sel_hi:[1,0]
	v_rcp_f32_e32 v152, v152
	v_rcp_f32_e32 v153, v153
	v_rcp_f32_e32 v160, v160
	v_rcp_f32_e32 v161, v161
	v_rcp_f32_e32 v164, v164
	v_rcp_f32_e32 v165, v165
	v_rcp_f32_e32 v168, v168
	v_rcp_f32_e32 v169, v169
	v_rcp_f32_e32 v172, v172
	v_rcp_f32_e32 v173, v173
	v_rcp_f32_e32 v176, v176
	v_rcp_f32_e32 v177, v177
	v_rcp_f32_e32 v180, v180
	v_rcp_f32_e32 v181, v181
	v_rcp_f32_e32 v184, v184
	v_rcp_f32_e32 v185, v185
	v_pk_mul_f32 v[44:45], v[44:45], v[152:153]
	v_pk_mul_f32 v[46:47], v[46:47], v[160:161]
	v_pk_mul_f32 v[40:41], v[40:41], v[164:165]
; __device__ __forceinline__ unsigned cvt_pk_bf16(float lo, float hi) { unsigned r; asm volatile("v_cvt_pk_bf16_f32 %0, %1, %2" : "=v"(r) : "v"(lo), "v"(hi)); return r; }
; __device__ __forceinline__ float fast_rcp(float x) { return __builtin_amdgcn_rcpf(x); }
; __device__ __forceinline__ unsigned cvt_pk_bf16(float lo, float hi) { const f32x2 v = {lo, hi}; const bf16x2_t b = __builtin_convertvector(v, bf16x2_t); return __builtin_bit_cast(unsigned, b); }
;     __device__ __forceinline__ void operator()(const f32x4 (&acc)[2][2][4][2], const Unit& u, int wr, int wc, int fr, int fq) const {
;     ...
;                 const int r = row0 + ai * HALF + m * 16; const float rs = rsv[ai][m];
;                 float s1 = 0.f, s2 = 0.f;
; #pragma unroll
;                 for (int bj = 0; bj < 2; ++bj) {
;                     f32x4 a = acc[ai][bj][m][0] * rs, b = acc[ai][bj][m][1] * rs;
;                     if (u.pn < gelu_tiles) {
; #pragma unroll
;                         for (int j = 0; j < 4; ++j) { const float ua = 1.5957691216057308f * a[j] * (1.0f + 0.044715f * a[j] * a[j]), ub = 1.5957691216057308f * b[j] * (1.0f + 0.044715f * b[j] * b[j]);
;                             a[j] = a[j] * fast_rcp(1.0f + __expf(-ua)); b[j] = b[j] * fast_rcp(1.0f + __expf(-ub)); }
;                     }
;                     if (va_tile) {
;                         s1 += ((a[0] + a[1]) + (a[2] + a[3])) + ((b[0] + b[1]) + (b[2] + b[3]));
;                         s2 += ((a[0] * a[0] + a[1] * a[1]) + (a[2] * a[2] + a[3] * a[3])) + ((b[0] * b[0] + b[1] * b[1]) + (b[2] * b[2] + b[3] * b[3]));
;                     }
;                     u32x4 w; w.x = cvt_pk_bf16(a[0], a[1]); w.y = cvt_pk_bf16(a[2], a[3]); w.z = cvt_pk_bf16(b[0], b[1]); w.w = cvt_pk_bf16(b[2], b[3]);
;                     *(u32x4*)(O + (size_t)r * ldo + col0 + bj * HALF) = w;
	v_pk_mul_f32 v[42:43], v[42:43], v[168:169]
	v_pk_mul_f32 v[36:37], v[36:37], v[172:173]
	v_pk_mul_f32 v[38:39], v[38:39], v[176:177]
	v_pk_mul_f32 v[32:33], v[32:33], v[180:181]
	v_pk_mul_f32 v[34:35], v[34:35], v[184:185]
	v_cvt_pk_bf16_f32 v44, v44, v45
	v_cvt_pk_bf16_f32 v45, v46, v47
	v_cvt_pk_bf16_f32 v46, v40, v41
	v_cvt_pk_bf16_f32 v47, v42, v43
	v_mad_i64_i32 v[216:217], s[90:91], v233, s80, v[212:213]
	v_lshl_add_u64 v[216:217], v[216:217], 0, v[210:211]
	global_store_dwordx4 v[216:217], v[44:47], off
	v_cvt_pk_bf16_f32 v36, v36, v37
	v_cvt_pk_bf16_f32 v37, v38, v39
	v_cvt_pk_bf16_f32 v38, v32, v33
	v_cvt_pk_bf16_f32 v39, v34, v35
	global_store_dwordx4 v[216:217], v[36:39], off offset:256
	v_pk_mul_f32 v[28:29], v[28:29], v[232:233] op_sel_hi:[1,0]
	v_pk_mul_f32 v[30:31], v[30:31], v[232:233] op_sel_hi:[1,0]
	v_pk_mul_f32 v[24:25], v[24:25], v[232:233] op_sel_hi:[1,0]
	v_pk_mul_f32 v[26:27], v[26:27], v[232:233] op_sel_hi:[1,0]
	v_pk_mul_f32 v[20:21], v[20:21], v[232:233] op_sel_hi:[1,0]
	v_pk_mul_f32 v[22:23], v[22:23], v[232:233] op_sel_hi:[1,0]
	v_pk_mul_f32 v[16:17], v[16:17], v[232:233] op_sel_hi:[1,0]
	v_pk_mul_f32 v[18:19], v[18:19], v[232:233] op_sel_hi:[1,0]
	v_pk_mul_f32 v[152:153], v[28:29], v[28:29]
	v_pk_mul_f32 v[160:161], v[30:31], v[30:31]
	v_pk_mul_f32 v[164:165], v[24:25], v[24:25]
	v_pk_mul_f32 v[168:169], v[26:27], v[26:27]
	v_pk_mul_f32 v[172:173], v[20:21], v[20:21]
	v_pk_mul_f32 v[176:177], v[22:23], v[22:23]
	v_pk_mul_f32 v[180:181], v[16:17], v[16:17]
	v_pk_mul_f32 v[184:185], v[18:19], v[18:19]
	v_pk_fma_f32 v[152:153], v[152:153], v[218:219], v[218:219] op_sel:[0,0,1] op_sel_hi:[1,0,1]
	v_pk_fma_f32 v[160:161], v[160:161], v[218:219], v[218:219] op_sel:[0,0,1] op_sel_hi:[1,0,1]
	v_pk_fma_f32 v[164:165], v[164:165], v[218:219], v[218:219] op_sel:[0,0,1] op_sel_hi:[1,0,1]
	v_pk_fma_f32 v[168:169], v[168:169], v[218:219], v[218:219] op_sel:[0,0,1] op_sel_hi:[1,0,1]
	v_pk_fma_f32 v[172:173], v[172:173], v[218:219], v[218:219] op_sel:[0,0,1] op_sel_hi:[1,0,1]
	v_pk_fma_f32 v[176:177], v[176:177], v[218:219], v[218:219] op_sel:[0,0,1] op_sel_hi:[1,0,1]
	v_pk_fma_f32 v[180:181], v[180:181], v[218:219], v[218:219] op_sel:[0,0,1] op_sel_hi:[1,0,1]
	v_pk_fma_f32 v[184:185], v[184:185], v[218:219], v[218:219] op_sel:[0,0,1] op_sel_hi:[1,0,1]
	v_pk_mul_f32 v[152:153], v[152:153], v[28:29]
	v_pk_mul_f32 v[160:161], v[160:161], v[30:31]
	v_pk_mul_f32 v[164:165], v[164:165], v[24:25]
	v_pk_mul_f32 v[168:169], v[168:169], v[26:27]
	v_pk_mul_f32 v[172:173], v[172:173], v[20:21]
	v_pk_mul_f32 v[176:177], v[176:177], v[22:23]
	v_pk_mul_f32 v[180:181], v[180:181], v[16:17]
	v_pk_mul_f32 v[184:185], v[184:185], v[18:19]
	v_exp_f32_e32 v152, v152
	v_exp_f32_e32 v153, v153
	v_exp_f32_e32 v160, v160
	v_exp_f32_e32 v161, v161
	v_exp_f32_e32 v164, v164
	v_exp_f32_e32 v165, v165
	v_exp_f32_e32 v168, v168
	v_exp_f32_e32 v169, v169
	v_exp_f32_e32 v172, v172
	v_exp_f32_e32 v173, v173
	v_exp_f32_e32 v176, v176
	v_exp_f32_e32 v177, v177
	v_exp_f32_e32 v180, v180
	v_exp_f32_e32 v181, v181
	v_exp_f32_e32 v184, v184
	v_exp_f32_e32 v185, v185
	v_pk_add_f32 v[152:153], v[152:153], 1.0 op_sel_hi:[1,0]
	v_pk_add_f32 v[160:161], v[160:161], 1.0 op_sel_hi:[1,0]
	v_pk_add_f32 v[164:165], v[164:165], 1.0 op_sel_hi:[1,0]
	v_pk_add_f32 v[168:169], v[168:169], 1.0 op_sel_hi:[1,0]
	v_pk_add_f32 v[172:173], v[172:173], 1.0 op_sel_hi:[1,0]
	v_pk_add_f32 v[176:177], v[176:177], 1.0 op_sel_hi:[1,0]
	v_pk_add_f32 v[180:181], v[180:181], 1.0 op_sel_hi:[1,0]
	v_pk_add_f32 v[184:185], v[184:185], 1.0 op_sel_hi:[1,0]
	v_rcp_f32_e32 v152, v152
	v_rcp_f32_e32 v153, v153
	v_rcp_f32_e32 v160, v160
	v_rcp_f32_e32 v161, v161
	v_rcp_f32_e32 v164, v164
	v_rcp_f32_e32 v165, v165
	v_rcp_f32_e32 v168, v168
	v_rcp_f32_e32 v169, v169
	v_rcp_f32_e32 v172, v172
	v_rcp_f32_e32 v173, v173
	v_rcp_f32_e32 v176, v176
	v_rcp_f32_e32 v177, v177
	v_rcp_f32_e32 v180, v180
	v_rcp_f32_e32 v181, v181
	v_rcp_f32_e32 v184, v184
	v_rcp_f32_e32 v185, v185
	v_pk_mul_f32 v[28:29], v[28:29], v[152:153]
	v_pk_mul_f32 v[30:31], v[30:31], v[160:161]
	v_pk_mul_f32 v[24:25], v[24:25], v[164:165]
	v_pk_mul_f32 v[26:27], v[26:27], v[168:169]
	v_pk_mul_f32 v[20:21], v[20:21], v[172:173]
	v_pk_mul_f32 v[22:23], v[22:23], v[176:177]
	v_pk_mul_f32 v[16:17], v[16:17], v[180:181]
	v_pk_mul_f32 v[18:19], v[18:19], v[184:185]
	v_cvt_pk_bf16_f32 v28, v28, v29
	v_cvt_pk_bf16_f32 v29, v30, v31
	v_cvt_pk_bf16_f32 v30, v24, v25
	v_cvt_pk_bf16_f32 v31, v26, v27
	v_mad_i64_i32 v[216:217], s[90:91], v235, s80, v[212:213]
	v_lshl_add_u64 v[216:217], v[216:217], 0, v[210:211]
	global_store_dwordx4 v[216:217], v[28:31], off
	v_cvt_pk_bf16_f32 v20, v20, v21
	v_cvt_pk_bf16_f32 v21, v22, v23
	v_cvt_pk_bf16_f32 v22, v16, v17
	v_cvt_pk_bf16_f32 v23, v18, v19
	global_store_dwordx4 v[216:217], v[20:23], off offset:256
	v_pk_mul_f32 v[12:13], v[12:13], v[234:235] op_sel_hi:[1,0]
	v_pk_mul_f32 v[14:15], v[14:15], v[234:235] op_sel_hi:[1,0]
	v_pk_mul_f32 v[8:9], v[8:9], v[234:235] op_sel_hi:[1,0]
	v_pk_mul_f32 v[10:11], v[10:11], v[234:235] op_sel_hi:[1,0]
	v_pk_mul_f32 v[4:5], v[4:5], v[234:235] op_sel_hi:[1,0]
	v_pk_mul_f32 v[6:7], v[6:7], v[234:235] op_sel_hi:[1,0]
	v_pk_mul_f32 v[0:1], v[0:1], v[234:235] op_sel_hi:[1,0]
	v_pk_mul_f32 v[2:3], v[2:3], v[234:235] op_sel_hi:[1,0]
	v_pk_mul_f32 v[152:153], v[12:13], v[12:13]
	v_pk_mul_f32 v[160:161], v[14:15], v[14:15]
	v_pk_mul_f32 v[164:165], v[8:9], v[8:9]
	v_pk_mul_f32 v[168:169], v[10:11], v[10:11]
	v_pk_mul_f32 v[172:173], v[4:5], v[4:5]
	v_pk_mul_f32 v[176:177], v[6:7], v[6:7]
	v_pk_mul_f32 v[180:181], v[0:1], v[0:1]
	v_pk_mul_f32 v[184:185], v[2:3], v[2:3]
; __device__ __forceinline__ unsigned cvt_pk_bf16(float lo, float hi) { unsigned r; asm volatile("v_cvt_pk_bf16_f32 %0, %1, %2" : "=v"(r) : "v"(lo), "v"(hi)); return r; }
; __device__ __forceinline__ float fast_rcp(float x) { return __builtin_amdgcn_rcpf(x); }
; __device__ __forceinline__ unsigned cvt_pk_bf16(float lo, float hi) { const f32x2 v = {lo, hi}; const bf16x2_t b = __builtin_convertvector(v, bf16x2_t); return __builtin_bit_cast(unsigned, b); }
;     __device__ __forceinline__ void operator()(const f32x4 (&acc)[2][2][4][2], const Unit& u, int wr, int wc, int fr, int fq) const {
;     ...
;                 const int r = row0 + ai * HALF + m * 16; const float rs = rsv[ai][m];
;                 float s1 = 0.f, s2 = 0.f;
; #pragma unroll
;                 for (int bj = 0; bj < 2; ++bj) {
;                     f32x4 a = acc[ai][bj][m][0] * rs, b = acc[ai][bj][m][1] * rs;
;                     if (u.pn < gelu_tiles) {
; #pragma unroll
;                         for (int j = 0; j < 4; ++j) { const float ua = 1.5957691216057308f * a[j] * (1.0f + 0.044715f * a[j] * a[j]), ub = 1.5957691216057308f * b[j] * (1.0f + 0.044715f * b[j] * b[j]);
;                             a[j] = a[j] * fast_rcp(1.0f + __expf(-ua)); b[j] = b[j] * fast_rcp(1.0f + __expf(-ub)); }
;                     }
;                     if (va_tile) {
;                         s1 += ((a[0] + a[1]) + (a[2] + a[3])) + ((b[0] + b[1]) + (b[2] + b[3]));
;                         s2 += ((a[0] * a[0] + a[1] * a[1]) + (a[2] * a[2] + a[3] * a[3])) + ((b[0] * b[0] + b[1] * b[1]) + (b[2] * b[2] + b[3] * b[3]));
;                     }
;                     u32x4 w; w.x = cvt_pk_bf16(a[0], a[1]); w.y = cvt_pk_bf16(a[2], a[3]); w.z = cvt_pk_bf16(b[0], b[1]); w.w = cvt_pk_bf16(b[2], b[3]);
;                     *(u32x4*)(O + (size_t)r * ldo + col0 + bj * HALF) = w;
;                 }
;                 if (va_tile) {
;                     s1 += __shfl_xor(s1, 16); s1 += __shfl_xor(s1, 32); s2 += __shfl_xor(s2, 16); s2 += __shfl_xor(s2, 32);
;                     if (fq == 0) *(f32x2*)(VS + (size_t)r * 16 + ((u.pn - 2) * 4 + wc) * 2) = (f32x2){s1, s2};
;                 }
	v_pk_fma_f32 v[152:153], v[152:153], v[218:219], v[218:219] op_sel:[0,0,1] op_sel_hi:[1,0,1]
	v_pk_fma_f32 v[160:161], v[160:161], v[218:219], v[218:219] op_sel:[0,0,1] op_sel_hi:[1,0,1]
	v_pk_fma_f32 v[164:165], v[164:165], v[218:219], v[218:219] op_sel:[0,0,1] op_sel_hi:[1,0,1]
	v_pk_fma_f32 v[168:169], v[168:169], v[218:219], v[218:219] op_sel:[0,0,1] op_sel_hi:[1,0,1]
	v_pk_fma_f32 v[172:173], v[172:173], v[218:219], v[218:219] op_sel:[0,0,1] op_sel_hi:[1,0,1]
	v_pk_fma_f32 v[176:177], v[176:177], v[218:219], v[218:219] op_sel:[0,0,1] op_sel_hi:[1,0,1]
	v_pk_fma_f32 v[180:181], v[180:181], v[218:219], v[218:219] op_sel:[0,0,1] op_sel_hi:[1,0,1]
	v_pk_fma_f32 v[184:185], v[184:185], v[218:219], v[218:219] op_sel:[0,0,1] op_sel_hi:[1,0,1]
	v_pk_mul_f32 v[152:153], v[152:153], v[12:13]
	v_pk_mul_f32 v[160:161], v[160:161], v[14:15]
	v_pk_mul_f32 v[164:165], v[164:165], v[8:9]
	v_pk_mul_f32 v[168:169], v[168:169], v[10:11]
	v_pk_mul_f32 v[172:173], v[172:173], v[4:5]
	v_pk_mul_f32 v[176:177], v[176:177], v[6:7]
	v_pk_mul_f32 v[180:181], v[180:181], v[0:1]
	v_pk_mul_f32 v[184:185], v[184:185], v[2:3]
	v_exp_f32_e32 v152, v152
	v_exp_f32_e32 v153, v153
	v_exp_f32_e32 v160, v160
	v_exp_f32_e32 v161, v161
	v_exp_f32_e32 v164, v164
	v_exp_f32_e32 v165, v165
	v_exp_f32_e32 v168, v168
	v_exp_f32_e32 v169, v169
	v_exp_f32_e32 v172, v172
	v_exp_f32_e32 v173, v173
	v_exp_f32_e32 v176, v176
	v_exp_f32_e32 v177, v177
	v_exp_f32_e32 v180, v180
	v_exp_f32_e32 v181, v181
	v_exp_f32_e32 v184, v184
	v_exp_f32_e32 v185, v185
	v_pk_add_f32 v[152:153], v[152:153], 1.0 op_sel_hi:[1,0]
	v_pk_add_f32 v[160:161], v[160:161], 1.0 op_sel_hi:[1,0]
	v_pk_add_f32 v[164:165], v[164:165], 1.0 op_sel_hi:[1,0]
	v_pk_add_f32 v[168:169], v[168:169], 1.0 op_sel_hi:[1,0]
	v_pk_add_f32 v[172:173], v[172:173], 1.0 op_sel_hi:[1,0]
	v_pk_add_f32 v[176:177], v[176:177], 1.0 op_sel_hi:[1,0]
	v_pk_add_f32 v[180:181], v[180:181], 1.0 op_sel_hi:[1,0]
	v_pk_add_f32 v[184:185], v[184:185], 1.0 op_sel_hi:[1,0]
	v_rcp_f32_e32 v152, v152
	v_rcp_f32_e32 v153, v153
	v_rcp_f32_e32 v160, v160
	v_rcp_f32_e32 v161, v161
	v_rcp_f32_e32 v164, v164
	v_rcp_f32_e32 v165, v165
	v_rcp_f32_e32 v168, v168
	v_rcp_f32_e32 v169, v169
	v_rcp_f32_e32 v172, v172
	v_rcp_f32_e32 v173, v173
	v_rcp_f32_e32 v176, v176
	v_rcp_f32_e32 v177, v177
	v_rcp_f32_e32 v180, v180
	v_rcp_f32_e32 v181, v181
	v_rcp_f32_e32 v184, v184
	v_rcp_f32_e32 v185, v185
	v_pk_mul_f32 v[12:13], v[12:13], v[152:153]
	v_pk_mul_f32 v[14:15], v[14:15], v[160:161]
	v_pk_mul_f32 v[8:9], v[8:9], v[164:165]
	v_pk_mul_f32 v[10:11], v[10:11], v[168:169]
	v_pk_mul_f32 v[4:5], v[4:5], v[172:173]
	v_pk_mul_f32 v[6:7], v[6:7], v[176:177]
	v_pk_mul_f32 v[0:1], v[0:1], v[180:181]
	v_pk_mul_f32 v[2:3], v[2:3], v[184:185]
	v_cvt_pk_bf16_f32 v12, v12, v13
	v_cvt_pk_bf16_f32 v13, v14, v15
	v_cvt_pk_bf16_f32 v14, v8, v9
	v_cvt_pk_bf16_f32 v15, v10, v11
	v_mad_i64_i32 v[216:217], s[90:91], v236, s80, v[212:213]
	v_lshl_add_u64 v[216:217], v[216:217], 0, v[210:211]
	global_store_dwordx4 v[216:217], v[12:15], off
	v_cvt_pk_bf16_f32 v4, v4, v5
	v_cvt_pk_bf16_f32 v5, v6, v7
	v_cvt_pk_bf16_f32 v6, v0, v1
	v_cvt_pk_bf16_f32 v7, v2, v3
	global_store_dwordx4 v[216:217], v[4:7], off offset:256
	s_branch .Lepiz_done_p3
.Lepiz_va_p3:
	v_pk_mul_f32 v[124:125], v[124:125], v[128:129] op_sel_hi:[1,0]
	v_pk_mul_f32 v[126:127], v[126:127], v[128:129] op_sel_hi:[1,0]
	v_pk_mul_f32 v[120:121], v[120:121], v[128:129] op_sel_hi:[1,0]
	v_pk_mul_f32 v[122:123], v[122:123], v[128:129] op_sel_hi:[1,0]
	v_pk_mul_f32 v[116:117], v[116:117], v[128:129] op_sel_hi:[1,0]
	v_pk_mul_f32 v[118:119], v[118:119], v[128:129] op_sel_hi:[1,0]
	v_pk_mul_f32 v[112:113], v[112:113], v[128:129] op_sel_hi:[1,0]
	v_pk_mul_f32 v[114:115], v[114:115], v[128:129] op_sel_hi:[1,0]
	v_pk_mul_f32 v[152:153], v[124:125], v[124:125]
	v_pk_mul_f32 v[160:161], v[126:127], v[126:127]
	v_pk_mul_f32 v[164:165], v[120:121], v[120:121]
	v_pk_mul_f32 v[168:169], v[122:123], v[122:123]
	v_pk_mul_f32 v[172:173], v[116:117], v[116:117]
	v_pk_mul_f32 v[176:177], v[118:119], v[118:119]
	v_pk_mul_f32 v[180:181], v[112:113], v[112:113]
	v_pk_mul_f32 v[184:185], v[114:115], v[114:115]
	v_pk_fma_f32 v[152:153], v[152:153], v[218:219], v[218:219] op_sel:[0,0,1] op_sel_hi:[1,0,1]
	v_pk_fma_f32 v[160:161], v[160:161], v[218:219], v[218:219] op_sel:[0,0,1] op_sel_hi:[1,0,1]
	v_pk_fma_f32 v[164:165], v[164:165], v[218:219], v[218:219] op_sel:[0,0,1] op_sel_hi:[1,0,1]
	v_pk_fma_f32 v[168:169], v[168:169], v[218:219], v[218:219] op_sel:[0,0,1] op_sel_hi:[1,0,1]
	v_pk_fma_f32 v[172:173], v[172:173], v[218:219], v[218:219] op_sel:[0,0,1] op_sel_hi:[1,0,1]
	v_pk_fma_f32 v[176:177], v[176:177], v[218:219], v[218:219] op_sel:[0,0,1] op_sel_hi:[1,0,1]
	v_pk_fma_f32 v[180:181], v[180:181], v[218:219], v[218:219] op_sel:[0,0,1] op_sel_hi:[1,0,1]
	v_pk_fma_f32 v[184:185], v[184:185], v[218:219], v[218:219] op_sel:[0,0,1] op_sel_hi:[1,0,1]
	v_pk_mul_f32 v[152:153], v[152:153], v[124:125]
	v_pk_mul_f32 v[160:161], v[160:161], v[126:127]
	v_pk_mul_f32 v[164:165], v[164:165], v[120:121]
	v_pk_mul_f32 v[168:169], v[168:169], v[122:123]
	v_pk_mul_f32 v[172:173], v[172:173], v[116:117]
	v_pk_mul_f32 v[176:177], v[176:177], v[118:119]
	v_pk_mul_f32 v[180:181], v[180:181], v[112:113]
	v_pk_mul_f32 v[184:185], v[184:185], v[114:115]
	v_exp_f32_e32 v152, v152
	v_exp_f32_e32 v153, v153
	v_exp_f32_e32 v160, v160
	v_exp_f32_e32 v161, v161
	v_exp_f32_e32 v164, v164
	v_exp_f32_e32 v165, v165
	v_exp_f32_e32 v168, v168
	v_exp_f32_e32 v169, v169
	v_exp_f32_e32 v172, v172
	v_exp_f32_e32 v173, v173
	v_exp_f32_e32 v176, v176
	v_exp_f32_e32 v177, v177
; __device__ __forceinline__ unsigned cvt_pk_bf16(float lo, float hi) { unsigned r; asm volatile("v_cvt_pk_bf16_f32 %0, %1, %2" : "=v"(r) : "v"(lo), "v"(hi)); return r; }
; __device__ __forceinline__ float fast_rcp(float x) { return __builtin_amdgcn_rcpf(x); }
; __device__ __forceinline__ unsigned cvt_pk_bf16(float lo, float hi) { const f32x2 v = {lo, hi}; const bf16x2_t b = __builtin_convertvector(v, bf16x2_t); return __builtin_bit_cast(unsigned, b); }
;     __device__ __forceinline__ void operator()(const f32x4 (&acc)[2][2][4][2], const Unit& u, int wr, int wc, int fr, int fq) const {
;     ...
;                 for (int bj = 0; bj < 2; ++bj) {
;                     f32x4 a = acc[ai][bj][m][0] * rs, b = acc[ai][bj][m][1] * rs;
;                     if (u.pn < gelu_tiles) {
; #pragma unroll
;                         for (int j = 0; j < 4; ++j) { const float ua = 1.5957691216057308f * a[j] * (1.0f + 0.044715f * a[j] * a[j]), ub = 1.5957691216057308f * b[j] * (1.0f + 0.044715f * b[j] * b[j]);
;                             a[j] = a[j] * fast_rcp(1.0f + __expf(-ua)); b[j] = b[j] * fast_rcp(1.0f + __expf(-ub)); }
;                     }
;                     if (va_tile) {
;                         s1 += ((a[0] + a[1]) + (a[2] + a[3])) + ((b[0] + b[1]) + (b[2] + b[3]));
;                         s2 += ((a[0] * a[0] + a[1] * a[1]) + (a[2] * a[2] + a[3] * a[3])) + ((b[0] * b[0] + b[1] * b[1]) + (b[2] * b[2] + b[3] * b[3]));
;                     }
;                     u32x4 w; w.x = cvt_pk_bf16(a[0], a[1]); w.y = cvt_pk_bf16(a[2], a[3]); w.z = cvt_pk_bf16(b[0], b[1]); w.w = cvt_pk_bf16(b[2], b[3]);
;                     *(u32x4*)(O + (size_t)r * ldo + col0 + bj * HALF) = w;
	v_exp_f32_e32 v180, v180
	v_exp_f32_e32 v181, v181
	v_exp_f32_e32 v184, v184
	v_exp_f32_e32 v185, v185
	v_pk_add_f32 v[152:153], v[152:153], 1.0 op_sel_hi:[1,0]
	v_pk_add_f32 v[160:161], v[160:161], 1.0 op_sel_hi:[1,0]
	v_pk_add_f32 v[164:165], v[164:165], 1.0 op_sel_hi:[1,0]
	v_pk_add_f32 v[168:169], v[168:169], 1.0 op_sel_hi:[1,0]
	v_pk_add_f32 v[172:173], v[172:173], 1.0 op_sel_hi:[1,0]
	v_pk_add_f32 v[176:177], v[176:177], 1.0 op_sel_hi:[1,0]
	v_pk_add_f32 v[180:181], v[180:181], 1.0 op_sel_hi:[1,0]
	v_pk_add_f32 v[184:185], v[184:185], 1.0 op_sel_hi:[1,0]
	v_rcp_f32_e32 v152, v152
	v_rcp_f32_e32 v153, v153
	v_rcp_f32_e32 v160, v160
	v_rcp_f32_e32 v161, v161
	v_rcp_f32_e32 v164, v164
	v_rcp_f32_e32 v165, v165
	v_rcp_f32_e32 v168, v168
	v_rcp_f32_e32 v169, v169
	v_rcp_f32_e32 v172, v172
	v_rcp_f32_e32 v173, v173
	v_rcp_f32_e32 v176, v176
	v_rcp_f32_e32 v177, v177
	v_rcp_f32_e32 v180, v180
	v_rcp_f32_e32 v181, v181
	v_rcp_f32_e32 v184, v184
	v_rcp_f32_e32 v185, v185
	v_pk_mul_f32 v[124:125], v[124:125], v[152:153]
	v_pk_mul_f32 v[126:127], v[126:127], v[160:161]
	v_pk_mul_f32 v[120:121], v[120:121], v[164:165]
	v_pk_mul_f32 v[122:123], v[122:123], v[168:169]
	v_pk_mul_f32 v[116:117], v[116:117], v[172:173]
	v_pk_mul_f32 v[118:119], v[118:119], v[176:177]
	v_pk_mul_f32 v[112:113], v[112:113], v[180:181]
	v_pk_mul_f32 v[114:115], v[114:115], v[184:185]
	v_pk_mul_f32 v[222:223], v[124:125], v[124:125]
	v_pk_add_f32 v[220:221], v[124:125], v[126:127]
	v_pk_fma_f32 v[222:223], v[126:127], v[126:127], v[222:223]
	v_pk_fma_f32 v[222:223], v[120:121], v[120:121], v[222:223]
	v_pk_add_f32 v[220:221], v[220:221], v[120:121]
	v_pk_fma_f32 v[222:223], v[122:123], v[122:123], v[222:223]
	v_pk_add_f32 v[220:221], v[220:221], v[122:123]
	v_pk_fma_f32 v[222:223], v[116:117], v[116:117], v[222:223]
	v_pk_add_f32 v[220:221], v[220:221], v[116:117]
	v_pk_fma_f32 v[222:223], v[118:119], v[118:119], v[222:223]
	v_pk_add_f32 v[220:221], v[220:221], v[118:119]
	v_pk_fma_f32 v[222:223], v[112:113], v[112:113], v[222:223]
	v_pk_add_f32 v[220:221], v[220:221], v[112:113]
	v_pk_fma_f32 v[222:223], v[114:115], v[114:115], v[222:223]
	v_pk_add_f32 v[220:221], v[220:221], v[114:115]
	v_add_f32_e32 v150, v220, v221
	v_add_f32_e32 v151, v222, v223
	v_cvt_pk_bf16_f32 v124, v124, v125
	v_cvt_pk_bf16_f32 v125, v126, v127
	v_cvt_pk_bf16_f32 v126, v120, v121
	v_cvt_pk_bf16_f32 v127, v122, v123
	v_mad_i64_i32 v[216:217], s[90:91], v208, s80, v[212:213]
	v_lshl_add_u64 v[216:217], v[216:217], 0, v[210:211]
	global_store_dwordx4 v[216:217], v[124:127], off
	v_cvt_pk_bf16_f32 v116, v116, v117
	v_cvt_pk_bf16_f32 v117, v118, v119
	v_cvt_pk_bf16_f32 v118, v112, v113
	v_cvt_pk_bf16_f32 v119, v114, v115
	global_store_dwordx4 v[216:217], v[116:119], off offset:256
	v_pk_mul_f32 v[108:109], v[108:109], v[158:159] op_sel_hi:[1,0]
	v_pk_mul_f32 v[110:111], v[110:111], v[158:159] op_sel_hi:[1,0]
	v_pk_mul_f32 v[104:105], v[104:105], v[158:159] op_sel_hi:[1,0]
	v_pk_mul_f32 v[106:107], v[106:107], v[158:159] op_sel_hi:[1,0]
	v_pk_mul_f32 v[100:101], v[100:101], v[158:159] op_sel_hi:[1,0]
	v_pk_mul_f32 v[102:103], v[102:103], v[158:159] op_sel_hi:[1,0]
	v_pk_mul_f32 v[96:97], v[96:97], v[158:159] op_sel_hi:[1,0]
	v_pk_mul_f32 v[98:99], v[98:99], v[158:159] op_sel_hi:[1,0]
	v_pk_mul_f32 v[152:153], v[108:109], v[108:109]
	v_pk_mul_f32 v[160:161], v[110:111], v[110:111]
	v_pk_mul_f32 v[164:165], v[104:105], v[104:105]
	v_pk_mul_f32 v[168:169], v[106:107], v[106:107]
	v_pk_mul_f32 v[172:173], v[100:101], v[100:101]
	v_pk_mul_f32 v[176:177], v[102:103], v[102:103]
	v_pk_mul_f32 v[180:181], v[96:97], v[96:97]
	v_pk_mul_f32 v[184:185], v[98:99], v[98:99]
	v_pk_fma_f32 v[152:153], v[152:153], v[218:219], v[218:219] op_sel:[0,0,1] op_sel_hi:[1,0,1]
	v_pk_fma_f32 v[160:161], v[160:161], v[218:219], v[218:219] op_sel:[0,0,1] op_sel_hi:[1,0,1]
	v_pk_fma_f32 v[164:165], v[164:165], v[218:219], v[218:219] op_sel:[0,0,1] op_sel_hi:[1,0,1]
	v_pk_fma_f32 v[168:169], v[168:169], v[218:219], v[218:219] op_sel:[0,0,1] op_sel_hi:[1,0,1]
	v_pk_fma_f32 v[172:173], v[172:173], v[218:219], v[218:219] op_sel:[0,0,1] op_sel_hi:[1,0,1]
	v_pk_fma_f32 v[176:177], v[176:177], v[218:219], v[218:219] op_sel:[0,0,1] op_sel_hi:[1,0,1]
	v_pk_fma_f32 v[180:181], v[180:181], v[218:219], v[218:219] op_sel:[0,0,1] op_sel_hi:[1,0,1]
	v_pk_fma_f32 v[184:185], v[184:185], v[218:219], v[218:219] op_sel:[0,0,1] op_sel_hi:[1,0,1]
	v_pk_mul_f32 v[152:153], v[152:153], v[108:109]
	v_pk_mul_f32 v[160:161], v[160:161], v[110:111]
	v_pk_mul_f32 v[164:165], v[164:165], v[104:105]
	v_pk_mul_f32 v[168:169], v[168:169], v[106:107]
	v_pk_mul_f32 v[172:173], v[172:173], v[100:101]
	v_pk_mul_f32 v[176:177], v[176:177], v[102:103]
	v_pk_mul_f32 v[180:181], v[180:181], v[96:97]
	v_pk_mul_f32 v[184:185], v[184:185], v[98:99]
	v_exp_f32_e32 v152, v152
	v_exp_f32_e32 v153, v153
	v_exp_f32_e32 v160, v160
	v_exp_f32_e32 v161, v161
	v_exp_f32_e32 v164, v164
	v_exp_f32_e32 v165, v165
	v_exp_f32_e32 v168, v168
	v_exp_f32_e32 v169, v169
	v_exp_f32_e32 v172, v172
	v_exp_f32_e32 v173, v173
	v_exp_f32_e32 v176, v176
	v_exp_f32_e32 v177, v177
	v_exp_f32_e32 v180, v180
	v_exp_f32_e32 v181, v181
	v_exp_f32_e32 v184, v184
	v_exp_f32_e32 v185, v185
	v_pk_add_f32 v[152:153], v[152:153], 1.0 op_sel_hi:[1,0]
	v_pk_add_f32 v[160:161], v[160:161], 1.0 op_sel_hi:[1,0]
	v_pk_add_f32 v[164:165], v[164:165], 1.0 op_sel_hi:[1,0]
	v_pk_add_f32 v[168:169], v[168:169], 1.0 op_sel_hi:[1,0]
	v_pk_add_f32 v[172:173], v[172:173], 1.0 op_sel_hi:[1,0]
	v_pk_add_f32 v[176:177], v[176:177], 1.0 op_sel_hi:[1,0]
	v_pk_add_f32 v[180:181], v[180:181], 1.0 op_sel_hi:[1,0]
; __device__ __forceinline__ unsigned cvt_pk_bf16(float lo, float hi) { unsigned r; asm volatile("v_cvt_pk_bf16_f32 %0, %1, %2" : "=v"(r) : "v"(lo), "v"(hi)); return r; }
; __device__ __forceinline__ float fast_rcp(float x) { return __builtin_amdgcn_rcpf(x); }
; __device__ __forceinline__ unsigned cvt_pk_bf16(float lo, float hi) { const f32x2 v = {lo, hi}; const bf16x2_t b = __builtin_convertvector(v, bf16x2_t); return __builtin_bit_cast(unsigned, b); }
;     __device__ __forceinline__ void operator()(const f32x4 (&acc)[2][2][4][2], const Unit& u, int wr, int wc, int fr, int fq) const {
;     ...
;                 for (int bj = 0; bj < 2; ++bj) {
;                     f32x4 a = acc[ai][bj][m][0] * rs, b = acc[ai][bj][m][1] * rs;
;                     if (u.pn < gelu_tiles) {
; #pragma unroll
;                         for (int j = 0; j < 4; ++j) { const float ua = 1.5957691216057308f * a[j] * (1.0f + 0.044715f * a[j] * a[j]), ub = 1.5957691216057308f * b[j] * (1.0f + 0.044715f * b[j] * b[j]);
;                             a[j] = a[j] * fast_rcp(1.0f + __expf(-ua)); b[j] = b[j] * fast_rcp(1.0f + __expf(-ub)); }
;                     }
;                     if (va_tile) {
;                         s1 += ((a[0] + a[1]) + (a[2] + a[3])) + ((b[0] + b[1]) + (b[2] + b[3]));
;                         s2 += ((a[0] * a[0] + a[1] * a[1]) + (a[2] * a[2] + a[3] * a[3])) + ((b[0] * b[0] + b[1] * b[1]) + (b[2] * b[2] + b[3] * b[3]));
;                     }
;                     u32x4 w; w.x = cvt_pk_bf16(a[0], a[1]); w.y = cvt_pk_bf16(a[2], a[3]); w.z = cvt_pk_bf16(b[0], b[1]); w.w = cvt_pk_bf16(b[2], b[3]);
;                     *(u32x4*)(O + (size_t)r * ldo + col0 + bj * HALF) = w;
	v_pk_add_f32 v[184:185], v[184:185], 1.0 op_sel_hi:[1,0]
	v_rcp_f32_e32 v152, v152
	v_rcp_f32_e32 v153, v153
	v_rcp_f32_e32 v160, v160
	v_rcp_f32_e32 v161, v161
	v_rcp_f32_e32 v164, v164
	v_rcp_f32_e32 v165, v165
	v_rcp_f32_e32 v168, v168
	v_rcp_f32_e32 v169, v169
	v_rcp_f32_e32 v172, v172
	v_rcp_f32_e32 v173, v173
	v_rcp_f32_e32 v176, v176
	v_rcp_f32_e32 v177, v177
	v_rcp_f32_e32 v180, v180
	v_rcp_f32_e32 v181, v181
	v_rcp_f32_e32 v184, v184
	v_rcp_f32_e32 v185, v185
	v_pk_mul_f32 v[108:109], v[108:109], v[152:153]
	v_pk_mul_f32 v[110:111], v[110:111], v[160:161]
	v_pk_mul_f32 v[104:105], v[104:105], v[164:165]
	v_pk_mul_f32 v[106:107], v[106:107], v[168:169]
	v_pk_mul_f32 v[100:101], v[100:101], v[172:173]
	v_pk_mul_f32 v[102:103], v[102:103], v[176:177]
	v_pk_mul_f32 v[96:97], v[96:97], v[180:181]
	v_pk_mul_f32 v[98:99], v[98:99], v[184:185]
	v_pk_mul_f32 v[222:223], v[108:109], v[108:109]
	v_pk_add_f32 v[220:221], v[108:109], v[110:111]
	v_pk_fma_f32 v[222:223], v[110:111], v[110:111], v[222:223]
	v_pk_fma_f32 v[222:223], v[104:105], v[104:105], v[222:223]
	v_pk_add_f32 v[220:221], v[220:221], v[104:105]
	v_pk_fma_f32 v[222:223], v[106:107], v[106:107], v[222:223]
	v_pk_add_f32 v[220:221], v[220:221], v[106:107]
	v_pk_fma_f32 v[222:223], v[100:101], v[100:101], v[222:223]
	v_pk_add_f32 v[220:221], v[220:221], v[100:101]
	v_pk_fma_f32 v[222:223], v[102:103], v[102:103], v[222:223]
	v_pk_add_f32 v[220:221], v[220:221], v[102:103]
	v_pk_fma_f32 v[222:223], v[96:97], v[96:97], v[222:223]
	v_pk_add_f32 v[220:221], v[220:221], v[96:97]
	v_pk_fma_f32 v[222:223], v[98:99], v[98:99], v[222:223]
	v_pk_add_f32 v[220:221], v[220:221], v[98:99]
	v_add_f32_e32 v156, v220, v221
	v_add_f32_e32 v157, v222, v223
	v_cvt_pk_bf16_f32 v108, v108, v109
	v_cvt_pk_bf16_f32 v109, v110, v111
	v_cvt_pk_bf16_f32 v110, v104, v105
	v_cvt_pk_bf16_f32 v111, v106, v107
	v_mad_i64_i32 v[216:217], s[90:91], v225, s80, v[212:213]
	v_lshl_add_u64 v[216:217], v[216:217], 0, v[210:211]
	global_store_dwordx4 v[216:217], v[108:111], off
	v_cvt_pk_bf16_f32 v100, v100, v101
	v_cvt_pk_bf16_f32 v101, v102, v103
	v_cvt_pk_bf16_f32 v102, v96, v97
	v_cvt_pk_bf16_f32 v103, v98, v99
	global_store_dwordx4 v[216:217], v[100:103], off offset:256
	v_pk_mul_f32 v[92:93], v[92:93], v[224:225] op_sel_hi:[1,0]
	v_pk_mul_f32 v[94:95], v[94:95], v[224:225] op_sel_hi:[1,0]
	v_pk_mul_f32 v[88:89], v[88:89], v[224:225] op_sel_hi:[1,0]
	v_pk_mul_f32 v[90:91], v[90:91], v[224:225] op_sel_hi:[1,0]
	v_pk_mul_f32 v[84:85], v[84:85], v[224:225] op_sel_hi:[1,0]
	v_pk_mul_f32 v[86:87], v[86:87], v[224:225] op_sel_hi:[1,0]
	v_pk_mul_f32 v[80:81], v[80:81], v[224:225] op_sel_hi:[1,0]
	v_pk_mul_f32 v[82:83], v[82:83], v[224:225] op_sel_hi:[1,0]
	v_pk_mul_f32 v[152:153], v[92:93], v[92:93]
	v_pk_mul_f32 v[160:161], v[94:95], v[94:95]
	v_pk_mul_f32 v[164:165], v[88:89], v[88:89]
	v_pk_mul_f32 v[168:169], v[90:91], v[90:91]
	v_pk_mul_f32 v[172:173], v[84:85], v[84:85]
	v_pk_mul_f32 v[176:177], v[86:87], v[86:87]
	v_pk_mul_f32 v[180:181], v[80:81], v[80:81]
	v_pk_mul_f32 v[184:185], v[82:83], v[82:83]
	v_pk_fma_f32 v[152:153], v[152:153], v[218:219], v[218:219] op_sel:[0,0,1] op_sel_hi:[1,0,1]
	v_pk_fma_f32 v[160:161], v[160:161], v[218:219], v[218:219] op_sel:[0,0,1] op_sel_hi:[1,0,1]
	v_pk_fma_f32 v[164:165], v[164:165], v[218:219], v[218:219] op_sel:[0,0,1] op_sel_hi:[1,0,1]
	v_pk_fma_f32 v[168:169], v[168:169], v[218:219], v[218:219] op_sel:[0,0,1] op_sel_hi:[1,0,1]
	v_pk_fma_f32 v[172:173], v[172:173], v[218:219], v[218:219] op_sel:[0,0,1] op_sel_hi:[1,0,1]
	v_pk_fma_f32 v[176:177], v[176:177], v[218:219], v[218:219] op_sel:[0,0,1] op_sel_hi:[1,0,1]
	v_pk_fma_f32 v[180:181], v[180:181], v[218:219], v[218:219] op_sel:[0,0,1] op_sel_hi:[1,0,1]
	v_pk_fma_f32 v[184:185], v[184:185], v[218:219], v[218:219] op_sel:[0,0,1] op_sel_hi:[1,0,1]
	v_pk_mul_f32 v[152:153], v[152:153], v[92:93]
	v_pk_mul_f32 v[160:161], v[160:161], v[94:95]
	v_pk_mul_f32 v[164:165], v[164:165], v[88:89]
	v_pk_mul_f32 v[168:169], v[168:169], v[90:91]
	v_pk_mul_f32 v[172:173], v[172:173], v[84:85]
	v_pk_mul_f32 v[176:177], v[176:177], v[86:87]
	v_pk_mul_f32 v[180:181], v[180:181], v[80:81]
	v_pk_mul_f32 v[184:185], v[184:185], v[82:83]
	v_exp_f32_e32 v152, v152
	v_exp_f32_e32 v153, v153
	v_exp_f32_e32 v160, v160
	v_exp_f32_e32 v161, v161
	v_exp_f32_e32 v164, v164
	v_exp_f32_e32 v165, v165
	v_exp_f32_e32 v168, v168
	v_exp_f32_e32 v169, v169
	v_exp_f32_e32 v172, v172
	v_exp_f32_e32 v173, v173
	v_exp_f32_e32 v176, v176
	v_exp_f32_e32 v177, v177
	v_exp_f32_e32 v180, v180
	v_exp_f32_e32 v181, v181
	v_exp_f32_e32 v184, v184
	v_exp_f32_e32 v185, v185
	v_pk_add_f32 v[152:153], v[152:153], 1.0 op_sel_hi:[1,0]
	v_pk_add_f32 v[160:161], v[160:161], 1.0 op_sel_hi:[1,0]
	v_pk_add_f32 v[164:165], v[164:165], 1.0 op_sel_hi:[1,0]
	v_pk_add_f32 v[168:169], v[168:169], 1.0 op_sel_hi:[1,0]
	v_pk_add_f32 v[172:173], v[172:173], 1.0 op_sel_hi:[1,0]
	v_pk_add_f32 v[176:177], v[176:177], 1.0 op_sel_hi:[1,0]
	v_pk_add_f32 v[180:181], v[180:181], 1.0 op_sel_hi:[1,0]
	v_pk_add_f32 v[184:185], v[184:185], 1.0 op_sel_hi:[1,0]
	v_rcp_f32_e32 v152, v152
	v_rcp_f32_e32 v153, v153
	v_rcp_f32_e32 v160, v160
	v_rcp_f32_e32 v161, v161
	v_rcp_f32_e32 v164, v164
	v_rcp_f32_e32 v165, v165
	v_rcp_f32_e32 v168, v168
	v_rcp_f32_e32 v169, v169
	v_rcp_f32_e32 v172, v172
	v_rcp_f32_e32 v173, v173
	v_rcp_f32_e32 v176, v176
	v_rcp_f32_e32 v177, v177
	v_rcp_f32_e32 v180, v180
	v_rcp_f32_e32 v181, v181
	v_rcp_f32_e32 v184, v184
	v_rcp_f32_e32 v185, v185
	v_pk_mul_f32 v[92:93], v[92:93], v[152:153]
	v_pk_mul_f32 v[94:95], v[94:95], v[160:161]
	v_pk_mul_f32 v[88:89], v[88:89], v[164:165]
; __device__ __forceinline__ unsigned cvt_pk_bf16(float lo, float hi) { unsigned r; asm volatile("v_cvt_pk_bf16_f32 %0, %1, %2" : "=v"(r) : "v"(lo), "v"(hi)); return r; }
; __device__ __forceinline__ float fast_rcp(float x) { return __builtin_amdgcn_rcpf(x); }
; __device__ __forceinline__ unsigned cvt_pk_bf16(float lo, float hi) { const f32x2 v = {lo, hi}; const bf16x2_t b = __builtin_convertvector(v, bf16x2_t); return __builtin_bit_cast(unsigned, b); }
;     __device__ __forceinline__ void operator()(const f32x4 (&acc)[2][2][4][2], const Unit& u, int wr, int wc, int fr, int fq) const {
;     ...
;                 for (int bj = 0; bj < 2; ++bj) {
;                     f32x4 a = acc[ai][bj][m][0] * rs, b = acc[ai][bj][m][1] * rs;
;                     if (u.pn < gelu_tiles) {
; #pragma unroll
;                         for (int j = 0; j < 4; ++j) { const float ua = 1.5957691216057308f * a[j] * (1.0f + 0.044715f * a[j] * a[j]), ub = 1.5957691216057308f * b[j] * (1.0f + 0.044715f * b[j] * b[j]);
;                             a[j] = a[j] * fast_rcp(1.0f + __expf(-ua)); b[j] = b[j] * fast_rcp(1.0f + __expf(-ub)); }
;                     }
;                     if (va_tile) {
;                         s1 += ((a[0] + a[1]) + (a[2] + a[3])) + ((b[0] + b[1]) + (b[2] + b[3]));
;                         s2 += ((a[0] * a[0] + a[1] * a[1]) + (a[2] * a[2] + a[3] * a[3])) + ((b[0] * b[0] + b[1] * b[1]) + (b[2] * b[2] + b[3] * b[3]));
;                     }
;                     u32x4 w; w.x = cvt_pk_bf16(a[0], a[1]); w.y = cvt_pk_bf16(a[2], a[3]); w.z = cvt_pk_bf16(b[0], b[1]); w.w = cvt_pk_bf16(b[2], b[3]);
;                     *(u32x4*)(O + (size_t)r * ldo + col0 + bj * HALF) = w;
	v_pk_mul_f32 v[90:91], v[90:91], v[168:169]
	v_pk_mul_f32 v[84:85], v[84:85], v[172:173]
	v_pk_mul_f32 v[86:87], v[86:87], v[176:177]
	v_pk_mul_f32 v[80:81], v[80:81], v[180:181]
	v_pk_mul_f32 v[82:83], v[82:83], v[184:185]
	v_pk_mul_f32 v[222:223], v[92:93], v[92:93]
	v_pk_add_f32 v[220:221], v[92:93], v[94:95]
	v_pk_fma_f32 v[222:223], v[94:95], v[94:95], v[222:223]
	v_pk_fma_f32 v[222:223], v[88:89], v[88:89], v[222:223]
	v_pk_add_f32 v[220:221], v[220:221], v[88:89]
	v_pk_fma_f32 v[222:223], v[90:91], v[90:91], v[222:223]
	v_pk_add_f32 v[220:221], v[220:221], v[90:91]
	v_pk_fma_f32 v[222:223], v[84:85], v[84:85], v[222:223]
	v_pk_add_f32 v[220:221], v[220:221], v[84:85]
	v_pk_fma_f32 v[222:223], v[86:87], v[86:87], v[222:223]
	v_pk_add_f32 v[220:221], v[220:221], v[86:87]
	v_pk_fma_f32 v[222:223], v[80:81], v[80:81], v[222:223]
	v_pk_add_f32 v[220:221], v[220:221], v[80:81]
	v_pk_fma_f32 v[222:223], v[82:83], v[82:83], v[222:223]
	v_pk_add_f32 v[220:221], v[220:221], v[82:83]
	v_add_f32_e32 v196, v220, v221
	v_add_f32_e32 v197, v222, v223
	v_cvt_pk_bf16_f32 v92, v92, v93
	v_cvt_pk_bf16_f32 v93, v94, v95
	v_cvt_pk_bf16_f32 v94, v88, v89
	v_cvt_pk_bf16_f32 v95, v90, v91
	v_mad_i64_i32 v[216:217], s[90:91], v227, s80, v[212:213]
	v_lshl_add_u64 v[216:217], v[216:217], 0, v[210:211]
	global_store_dwordx4 v[216:217], v[92:95], off
	v_cvt_pk_bf16_f32 v84, v84, v85
	v_cvt_pk_bf16_f32 v85, v86, v87
	v_cvt_pk_bf16_f32 v86, v80, v81
	v_cvt_pk_bf16_f32 v87, v82, v83
	global_store_dwordx4 v[216:217], v[84:87], off offset:256
	v_pk_mul_f32 v[76:77], v[76:77], v[226:227] op_sel_hi:[1,0]
	v_pk_mul_f32 v[78:79], v[78:79], v[226:227] op_sel_hi:[1,0]
	v_pk_mul_f32 v[72:73], v[72:73], v[226:227] op_sel_hi:[1,0]
	v_pk_mul_f32 v[74:75], v[74:75], v[226:227] op_sel_hi:[1,0]
	v_pk_mul_f32 v[68:69], v[68:69], v[226:227] op_sel_hi:[1,0]
	v_pk_mul_f32 v[70:71], v[70:71], v[226:227] op_sel_hi:[1,0]
	v_pk_mul_f32 v[64:65], v[64:65], v[226:227] op_sel_hi:[1,0]
	v_pk_mul_f32 v[66:67], v[66:67], v[226:227] op_sel_hi:[1,0]
	v_pk_mul_f32 v[152:153], v[76:77], v[76:77]
	v_pk_mul_f32 v[160:161], v[78:79], v[78:79]
	v_pk_mul_f32 v[164:165], v[72:73], v[72:73]
	v_pk_mul_f32 v[168:169], v[74:75], v[74:75]
	v_pk_mul_f32 v[172:173], v[68:69], v[68:69]
	v_pk_mul_f32 v[176:177], v[70:71], v[70:71]
	v_pk_mul_f32 v[180:181], v[64:65], v[64:65]
	v_pk_mul_f32 v[184:185], v[66:67], v[66:67]
	v_pk_fma_f32 v[152:153], v[152:153], v[218:219], v[218:219] op_sel:[0,0,1] op_sel_hi:[1,0,1]
	v_pk_fma_f32 v[160:161], v[160:161], v[218:219], v[218:219] op_sel:[0,0,1] op_sel_hi:[1,0,1]
	v_pk_fma_f32 v[164:165], v[164:165], v[218:219], v[218:219] op_sel:[0,0,1] op_sel_hi:[1,0,1]
	v_pk_fma_f32 v[168:169], v[168:169], v[218:219], v[218:219] op_sel:[0,0,1] op_sel_hi:[1,0,1]
	v_pk_fma_f32 v[172:173], v[172:173], v[218:219], v[218:219] op_sel:[0,0,1] op_sel_hi:[1,0,1]
	v_pk_fma_f32 v[176:177], v[176:177], v[218:219], v[218:219] op_sel:[0,0,1] op_sel_hi:[1,0,1]
	v_pk_fma_f32 v[180:181], v[180:181], v[218:219], v[218:219] op_sel:[0,0,1] op_sel_hi:[1,0,1]
	v_pk_fma_f32 v[184:185], v[184:185], v[218:219], v[218:219] op_sel:[0,0,1] op_sel_hi:[1,0,1]
	v_pk_mul_f32 v[152:153], v[152:153], v[76:77]
	v_pk_mul_f32 v[160:161], v[160:161], v[78:79]
	v_pk_mul_f32 v[164:165], v[164:165], v[72:73]
	v_pk_mul_f32 v[168:169], v[168:169], v[74:75]
	v_pk_mul_f32 v[172:173], v[172:173], v[68:69]
	v_pk_mul_f32 v[176:177], v[176:177], v[70:71]
	v_pk_mul_f32 v[180:181], v[180:181], v[64:65]
	v_pk_mul_f32 v[184:185], v[184:185], v[66:67]
	v_exp_f32_e32 v152, v152
	v_exp_f32_e32 v153, v153
	v_exp_f32_e32 v160, v160
	v_exp_f32_e32 v161, v161
	v_exp_f32_e32 v164, v164
	v_exp_f32_e32 v165, v165
	v_exp_f32_e32 v168, v168
	v_exp_f32_e32 v169, v169
	v_exp_f32_e32 v172, v172
	v_exp_f32_e32 v173, v173
	v_exp_f32_e32 v176, v176
	v_exp_f32_e32 v177, v177
	v_exp_f32_e32 v180, v180
	v_exp_f32_e32 v181, v181
	v_exp_f32_e32 v184, v184
	v_exp_f32_e32 v185, v185
	v_pk_add_f32 v[152:153], v[152:153], 1.0 op_sel_hi:[1,0]
	v_pk_add_f32 v[160:161], v[160:161], 1.0 op_sel_hi:[1,0]
	v_pk_add_f32 v[164:165], v[164:165], 1.0 op_sel_hi:[1,0]
	v_pk_add_f32 v[168:169], v[168:169], 1.0 op_sel_hi:[1,0]
	v_pk_add_f32 v[172:173], v[172:173], 1.0 op_sel_hi:[1,0]
	v_pk_add_f32 v[176:177], v[176:177], 1.0 op_sel_hi:[1,0]
	v_pk_add_f32 v[180:181], v[180:181], 1.0 op_sel_hi:[1,0]
	v_pk_add_f32 v[184:185], v[184:185], 1.0 op_sel_hi:[1,0]
	v_rcp_f32_e32 v152, v152
	v_rcp_f32_e32 v153, v153
	v_rcp_f32_e32 v160, v160
	v_rcp_f32_e32 v161, v161
	v_rcp_f32_e32 v164, v164
	v_rcp_f32_e32 v165, v165
	v_rcp_f32_e32 v168, v168
	v_rcp_f32_e32 v169, v169
	v_rcp_f32_e32 v172, v172
	v_rcp_f32_e32 v173, v173
	v_rcp_f32_e32 v176, v176
	v_rcp_f32_e32 v177, v177
	v_rcp_f32_e32 v180, v180
	v_rcp_f32_e32 v181, v181
	v_rcp_f32_e32 v184, v184
	v_rcp_f32_e32 v185, v185
	v_pk_mul_f32 v[76:77], v[76:77], v[152:153]
	v_pk_mul_f32 v[78:79], v[78:79], v[160:161]
	v_pk_mul_f32 v[72:73], v[72:73], v[164:165]
	v_pk_mul_f32 v[74:75], v[74:75], v[168:169]
	v_pk_mul_f32 v[68:69], v[68:69], v[172:173]
	v_pk_mul_f32 v[70:71], v[70:71], v[176:177]
	v_pk_mul_f32 v[64:65], v[64:65], v[180:181]
	v_pk_mul_f32 v[66:67], v[66:67], v[184:185]
	v_pk_mul_f32 v[222:223], v[76:77], v[76:77]
	v_pk_add_f32 v[220:221], v[76:77], v[78:79]
	v_pk_fma_f32 v[222:223], v[78:79], v[78:79], v[222:223]
	v_pk_fma_f32 v[222:223], v[72:73], v[72:73], v[222:223]
	v_pk_add_f32 v[220:221], v[220:221], v[72:73]
	v_pk_fma_f32 v[222:223], v[74:75], v[74:75], v[222:223]
	v_pk_add_f32 v[220:221], v[220:221], v[74:75]
	v_pk_fma_f32 v[222:223], v[68:69], v[68:69], v[222:223]
	v_pk_add_f32 v[220:221], v[220:221], v[68:69]
; __device__ __forceinline__ unsigned cvt_pk_bf16(float lo, float hi) { unsigned r; asm volatile("v_cvt_pk_bf16_f32 %0, %1, %2" : "=v"(r) : "v"(lo), "v"(hi)); return r; }
; __device__ __forceinline__ float fast_rcp(float x) { return __builtin_amdgcn_rcpf(x); }
; __device__ __forceinline__ unsigned cvt_pk_bf16(float lo, float hi) { const f32x2 v = {lo, hi}; const bf16x2_t b = __builtin_convertvector(v, bf16x2_t); return __builtin_bit_cast(unsigned, b); }
;     __device__ __forceinline__ void operator()(const f32x4 (&acc)[2][2][4][2], const Unit& u, int wr, int wc, int fr, int fq) const {
;     ...
;                 for (int bj = 0; bj < 2; ++bj) {
;                     f32x4 a = acc[ai][bj][m][0] * rs, b = acc[ai][bj][m][1] * rs;
;                     if (u.pn < gelu_tiles) {
; #pragma unroll
;                         for (int j = 0; j < 4; ++j) { const float ua = 1.5957691216057308f * a[j] * (1.0f + 0.044715f * a[j] * a[j]), ub = 1.5957691216057308f * b[j] * (1.0f + 0.044715f * b[j] * b[j]);
;                             a[j] = a[j] * fast_rcp(1.0f + __expf(-ua)); b[j] = b[j] * fast_rcp(1.0f + __expf(-ub)); }
;                     }
;                     if (va_tile) {
;                         s1 += ((a[0] + a[1]) + (a[2] + a[3])) + ((b[0] + b[1]) + (b[2] + b[3]));
;                         s2 += ((a[0] * a[0] + a[1] * a[1]) + (a[2] * a[2] + a[3] * a[3])) + ((b[0] * b[0] + b[1] * b[1]) + (b[2] * b[2] + b[3] * b[3]));
;                     }
;                     u32x4 w; w.x = cvt_pk_bf16(a[0], a[1]); w.y = cvt_pk_bf16(a[2], a[3]); w.z = cvt_pk_bf16(b[0], b[1]); w.w = cvt_pk_bf16(b[2], b[3]);
;                     *(u32x4*)(O + (size_t)r * ldo + col0 + bj * HALF) = w;
	v_pk_fma_f32 v[222:223], v[70:71], v[70:71], v[222:223]
	v_pk_add_f32 v[220:221], v[220:221], v[70:71]
	v_pk_fma_f32 v[222:223], v[64:65], v[64:65], v[222:223]
	v_pk_add_f32 v[220:221], v[220:221], v[64:65]
	v_pk_fma_f32 v[222:223], v[66:67], v[66:67], v[222:223]
	v_pk_add_f32 v[220:221], v[220:221], v[66:67]
	v_add_f32_e32 v198, v220, v221
	v_add_f32_e32 v199, v222, v223
	v_cvt_pk_bf16_f32 v76, v76, v77
	v_cvt_pk_bf16_f32 v77, v78, v79
	v_cvt_pk_bf16_f32 v78, v72, v73
	v_cvt_pk_bf16_f32 v79, v74, v75
	v_mad_i64_i32 v[216:217], s[90:91], v229, s80, v[212:213]
	v_lshl_add_u64 v[216:217], v[216:217], 0, v[210:211]
	global_store_dwordx4 v[216:217], v[76:79], off
	v_cvt_pk_bf16_f32 v68, v68, v69
	v_cvt_pk_bf16_f32 v69, v70, v71
	v_cvt_pk_bf16_f32 v70, v64, v65
	v_cvt_pk_bf16_f32 v71, v66, v67
	global_store_dwordx4 v[216:217], v[68:71], off offset:256
	v_pk_mul_f32 v[60:61], v[60:61], v[228:229] op_sel_hi:[1,0]
	v_pk_mul_f32 v[62:63], v[62:63], v[228:229] op_sel_hi:[1,0]
	v_pk_mul_f32 v[56:57], v[56:57], v[228:229] op_sel_hi:[1,0]
	v_pk_mul_f32 v[58:59], v[58:59], v[228:229] op_sel_hi:[1,0]
	v_pk_mul_f32 v[52:53], v[52:53], v[228:229] op_sel_hi:[1,0]
	v_pk_mul_f32 v[54:55], v[54:55], v[228:229] op_sel_hi:[1,0]
	v_pk_mul_f32 v[48:49], v[48:49], v[228:229] op_sel_hi:[1,0]
	v_pk_mul_f32 v[50:51], v[50:51], v[228:229] op_sel_hi:[1,0]
	v_pk_mul_f32 v[152:153], v[60:61], v[60:61]
	v_pk_mul_f32 v[160:161], v[62:63], v[62:63]
	v_pk_mul_f32 v[164:165], v[56:57], v[56:57]
	v_pk_mul_f32 v[168:169], v[58:59], v[58:59]
	v_pk_mul_f32 v[172:173], v[52:53], v[52:53]
	v_pk_mul_f32 v[176:177], v[54:55], v[54:55]
	v_pk_mul_f32 v[180:181], v[48:49], v[48:49]
	v_pk_mul_f32 v[184:185], v[50:51], v[50:51]
	v_pk_fma_f32 v[152:153], v[152:153], v[218:219], v[218:219] op_sel:[0,0,1] op_sel_hi:[1,0,1]
	v_pk_fma_f32 v[160:161], v[160:161], v[218:219], v[218:219] op_sel:[0,0,1] op_sel_hi:[1,0,1]
	v_pk_fma_f32 v[164:165], v[164:165], v[218:219], v[218:219] op_sel:[0,0,1] op_sel_hi:[1,0,1]
	v_pk_fma_f32 v[168:169], v[168:169], v[218:219], v[218:219] op_sel:[0,0,1] op_sel_hi:[1,0,1]
	v_pk_fma_f32 v[172:173], v[172:173], v[218:219], v[218:219] op_sel:[0,0,1] op_sel_hi:[1,0,1]
	v_pk_fma_f32 v[176:177], v[176:177], v[218:219], v[218:219] op_sel:[0,0,1] op_sel_hi:[1,0,1]
	v_pk_fma_f32 v[180:181], v[180:181], v[218:219], v[218:219] op_sel:[0,0,1] op_sel_hi:[1,0,1]
	v_pk_fma_f32 v[184:185], v[184:185], v[218:219], v[218:219] op_sel:[0,0,1] op_sel_hi:[1,0,1]
	v_pk_mul_f32 v[152:153], v[152:153], v[60:61]
	v_pk_mul_f32 v[160:161], v[160:161], v[62:63]
	v_pk_mul_f32 v[164:165], v[164:165], v[56:57]
	v_pk_mul_f32 v[168:169], v[168:169], v[58:59]
	v_pk_mul_f32 v[172:173], v[172:173], v[52:53]
	v_pk_mul_f32 v[176:177], v[176:177], v[54:55]
	v_pk_mul_f32 v[180:181], v[180:181], v[48:49]
	v_pk_mul_f32 v[184:185], v[184:185], v[50:51]
	v_exp_f32_e32 v152, v152
	v_exp_f32_e32 v153, v153
	v_exp_f32_e32 v160, v160
	v_exp_f32_e32 v161, v161
	v_exp_f32_e32 v164, v164
	v_exp_f32_e32 v165, v165
	v_exp_f32_e32 v168, v168
	v_exp_f32_e32 v169, v169
	v_exp_f32_e32 v172, v172
	v_exp_f32_e32 v173, v173
	v_exp_f32_e32 v176, v176
	v_exp_f32_e32 v177, v177
	v_exp_f32_e32 v180, v180
	v_exp_f32_e32 v181, v181
	v_exp_f32_e32 v184, v184
	v_exp_f32_e32 v185, v185
	v_pk_add_f32 v[152:153], v[152:153], 1.0 op_sel_hi:[1,0]
	v_pk_add_f32 v[160:161], v[160:161], 1.0 op_sel_hi:[1,0]
	v_pk_add_f32 v[164:165], v[164:165], 1.0 op_sel_hi:[1,0]
	v_pk_add_f32 v[168:169], v[168:169], 1.0 op_sel_hi:[1,0]
	v_pk_add_f32 v[172:173], v[172:173], 1.0 op_sel_hi:[1,0]
	v_pk_add_f32 v[176:177], v[176:177], 1.0 op_sel_hi:[1,0]
	v_pk_add_f32 v[180:181], v[180:181], 1.0 op_sel_hi:[1,0]
	v_pk_add_f32 v[184:185], v[184:185], 1.0 op_sel_hi:[1,0]
	v_rcp_f32_e32 v152, v152
	v_rcp_f32_e32 v153, v153
	v_rcp_f32_e32 v160, v160
	v_rcp_f32_e32 v161, v161
	v_rcp_f32_e32 v164, v164
	v_rcp_f32_e32 v165, v165
	v_rcp_f32_e32 v168, v168
	v_rcp_f32_e32 v169, v169
	v_rcp_f32_e32 v172, v172
	v_rcp_f32_e32 v173, v173
	v_rcp_f32_e32 v176, v176
	v_rcp_f32_e32 v177, v177
	v_rcp_f32_e32 v180, v180
	v_rcp_f32_e32 v181, v181
	v_rcp_f32_e32 v184, v184
	v_rcp_f32_e32 v185, v185
	v_pk_mul_f32 v[60:61], v[60:61], v[152:153]
	v_pk_mul_f32 v[62:63], v[62:63], v[160:161]
	v_pk_mul_f32 v[56:57], v[56:57], v[164:165]
	v_pk_mul_f32 v[58:59], v[58:59], v[168:169]
	v_pk_mul_f32 v[52:53], v[52:53], v[172:173]
	v_pk_mul_f32 v[54:55], v[54:55], v[176:177]
	v_pk_mul_f32 v[48:49], v[48:49], v[180:181]
	v_pk_mul_f32 v[50:51], v[50:51], v[184:185]
	v_pk_mul_f32 v[222:223], v[60:61], v[60:61]
	v_pk_add_f32 v[220:221], v[60:61], v[62:63]
	v_pk_fma_f32 v[222:223], v[62:63], v[62:63], v[222:223]
	v_pk_fma_f32 v[222:223], v[56:57], v[56:57], v[222:223]
	v_pk_add_f32 v[220:221], v[220:221], v[56:57]
	v_pk_fma_f32 v[222:223], v[58:59], v[58:59], v[222:223]
	v_pk_add_f32 v[220:221], v[220:221], v[58:59]
	v_pk_fma_f32 v[222:223], v[52:53], v[52:53], v[222:223]
	v_pk_add_f32 v[220:221], v[220:221], v[52:53]
	v_pk_fma_f32 v[222:223], v[54:55], v[54:55], v[222:223]
	v_pk_add_f32 v[220:221], v[220:221], v[54:55]
	v_pk_fma_f32 v[222:223], v[48:49], v[48:49], v[222:223]
	v_pk_add_f32 v[220:221], v[220:221], v[48:49]
	v_pk_fma_f32 v[222:223], v[50:51], v[50:51], v[222:223]
	v_pk_add_f32 v[220:221], v[220:221], v[50:51]
	v_add_f32_e32 v200, v220, v221
	v_add_f32_e32 v201, v222, v223
	v_cvt_pk_bf16_f32 v60, v60, v61
	v_cvt_pk_bf16_f32 v61, v62, v63
	v_cvt_pk_bf16_f32 v62, v56, v57
	v_cvt_pk_bf16_f32 v63, v58, v59
	v_mad_i64_i32 v[216:217], s[90:91], v231, s80, v[212:213]
	v_lshl_add_u64 v[216:217], v[216:217], 0, v[210:211]
	global_store_dwordx4 v[216:217], v[60:63], off
	v_cvt_pk_bf16_f32 v52, v52, v53
; __device__ __forceinline__ unsigned cvt_pk_bf16(float lo, float hi) { unsigned r; asm volatile("v_cvt_pk_bf16_f32 %0, %1, %2" : "=v"(r) : "v"(lo), "v"(hi)); return r; }
; __device__ __forceinline__ float fast_rcp(float x) { return __builtin_amdgcn_rcpf(x); }
; __device__ __forceinline__ unsigned cvt_pk_bf16(float lo, float hi) { const f32x2 v = {lo, hi}; const bf16x2_t b = __builtin_convertvector(v, bf16x2_t); return __builtin_bit_cast(unsigned, b); }
;     __device__ __forceinline__ void operator()(const f32x4 (&acc)[2][2][4][2], const Unit& u, int wr, int wc, int fr, int fq) const {
;     ...
;                 for (int bj = 0; bj < 2; ++bj) {
;                     f32x4 a = acc[ai][bj][m][0] * rs, b = acc[ai][bj][m][1] * rs;
;                     if (u.pn < gelu_tiles) {
; #pragma unroll
;                         for (int j = 0; j < 4; ++j) { const float ua = 1.5957691216057308f * a[j] * (1.0f + 0.044715f * a[j] * a[j]), ub = 1.5957691216057308f * b[j] * (1.0f + 0.044715f * b[j] * b[j]);
;                             a[j] = a[j] * fast_rcp(1.0f + __expf(-ua)); b[j] = b[j] * fast_rcp(1.0f + __expf(-ub)); }
;                     }
;                     if (va_tile) {
;                         s1 += ((a[0] + a[1]) + (a[2] + a[3])) + ((b[0] + b[1]) + (b[2] + b[3]));
;                         s2 += ((a[0] * a[0] + a[1] * a[1]) + (a[2] * a[2] + a[3] * a[3])) + ((b[0] * b[0] + b[1] * b[1]) + (b[2] * b[2] + b[3] * b[3]));
;                     }
;                     u32x4 w; w.x = cvt_pk_bf16(a[0], a[1]); w.y = cvt_pk_bf16(a[2], a[3]); w.z = cvt_pk_bf16(b[0], b[1]); w.w = cvt_pk_bf16(b[2], b[3]);
;                     *(u32x4*)(O + (size_t)r * ldo + col0 + bj * HALF) = w;
	v_cvt_pk_bf16_f32 v53, v54, v55
	v_cvt_pk_bf16_f32 v54, v48, v49
	v_cvt_pk_bf16_f32 v55, v50, v51
	global_store_dwordx4 v[216:217], v[52:55], off offset:256
	v_pk_mul_f32 v[44:45], v[44:45], v[230:231] op_sel_hi:[1,0]
	v_pk_mul_f32 v[46:47], v[46:47], v[230:231] op_sel_hi:[1,0]
	v_pk_mul_f32 v[40:41], v[40:41], v[230:231] op_sel_hi:[1,0]
	v_pk_mul_f32 v[42:43], v[42:43], v[230:231] op_sel_hi:[1,0]
	v_pk_mul_f32 v[36:37], v[36:37], v[230:231] op_sel_hi:[1,0]
	v_pk_mul_f32 v[38:39], v[38:39], v[230:231] op_sel_hi:[1,0]
	v_pk_mul_f32 v[32:33], v[32:33], v[230:231] op_sel_hi:[1,0]
	v_pk_mul_f32 v[34:35], v[34:35], v[230:231] op_sel_hi:[1,0]
	v_pk_mul_f32 v[152:153], v[44:45], v[44:45]
	v_pk_mul_f32 v[160:161], v[46:47], v[46:47]
	v_pk_mul_f32 v[164:165], v[40:41], v[40:41]
	v_pk_mul_f32 v[168:169], v[42:43], v[42:43]
	v_pk_mul_f32 v[172:173], v[36:37], v[36:37]
	v_pk_mul_f32 v[176:177], v[38:39], v[38:39]
	v_pk_mul_f32 v[180:181], v[32:33], v[32:33]
	v_pk_mul_f32 v[184:185], v[34:35], v[34:35]
	v_pk_fma_f32 v[152:153], v[152:153], v[218:219], v[218:219] op_sel:[0,0,1] op_sel_hi:[1,0,1]
	v_pk_fma_f32 v[160:161], v[160:161], v[218:219], v[218:219] op_sel:[0,0,1] op_sel_hi:[1,0,1]
	v_pk_fma_f32 v[164:165], v[164:165], v[218:219], v[218:219] op_sel:[0,0,1] op_sel_hi:[1,0,1]
	v_pk_fma_f32 v[168:169], v[168:169], v[218:219], v[218:219] op_sel:[0,0,1] op_sel_hi:[1,0,1]
	v_pk_fma_f32 v[172:173], v[172:173], v[218:219], v[218:219] op_sel:[0,0,1] op_sel_hi:[1,0,1]
	v_pk_fma_f32 v[176:177], v[176:177], v[218:219], v[218:219] op_sel:[0,0,1] op_sel_hi:[1,0,1]
	v_pk_fma_f32 v[180:181], v[180:181], v[218:219], v[218:219] op_sel:[0,0,1] op_sel_hi:[1,0,1]
	v_pk_fma_f32 v[184:185], v[184:185], v[218:219], v[218:219] op_sel:[0,0,1] op_sel_hi:[1,0,1]
	v_pk_mul_f32 v[152:153], v[152:153], v[44:45]
	v_pk_mul_f32 v[160:161], v[160:161], v[46:47]
	v_pk_mul_f32 v[164:165], v[164:165], v[40:41]
	v_pk_mul_f32 v[168:169], v[168:169], v[42:43]
	v_pk_mul_f32 v[172:173], v[172:173], v[36:37]
	v_pk_mul_f32 v[176:177], v[176:177], v[38:39]
	v_pk_mul_f32 v[180:181], v[180:181], v[32:33]
	v_pk_mul_f32 v[184:185], v[184:185], v[34:35]
	v_exp_f32_e32 v152, v152
	v_exp_f32_e32 v153, v153
	v_exp_f32_e32 v160, v160
	v_exp_f32_e32 v161, v161
	v_exp_f32_e32 v164, v164
	v_exp_f32_e32 v165, v165
	v_exp_f32_e32 v168, v168
	v_exp_f32_e32 v169, v169
	v_exp_f32_e32 v172, v172
	v_exp_f32_e32 v173, v173
	v_exp_f32_e32 v176, v176
	v_exp_f32_e32 v177, v177
	v_exp_f32_e32 v180, v180
	v_exp_f32_e32 v181, v181
	v_exp_f32_e32 v184, v184
	v_exp_f32_e32 v185, v185
	v_pk_add_f32 v[152:153], v[152:153], 1.0 op_sel_hi:[1,0]
	v_pk_add_f32 v[160:161], v[160:161], 1.0 op_sel_hi:[1,0]
	v_pk_add_f32 v[164:165], v[164:165], 1.0 op_sel_hi:[1,0]
	v_pk_add_f32 v[168:169], v[168:169], 1.0 op_sel_hi:[1,0]
	v_pk_add_f32 v[172:173], v[172:173], 1.0 op_sel_hi:[1,0]
	v_pk_add_f32 v[176:177], v[176:177], 1.0 op_sel_hi:[1,0]
	v_pk_add_f32 v[180:181], v[180:181], 1.0 op_sel_hi:[1,0]
	v_pk_add_f32 v[184:185], v[184:185], 1.0 op_sel_hi:[1,0]
	v_rcp_f32_e32 v152, v152
	v_rcp_f32_e32 v153, v153
	v_rcp_f32_e32 v160, v160
	v_rcp_f32_e32 v161, v161
	v_rcp_f32_e32 v164, v164
	v_rcp_f32_e32 v165, v165
	v_rcp_f32_e32 v168, v168
	v_rcp_f32_e32 v169, v169
	v_rcp_f32_e32 v172, v172
	v_rcp_f32_e32 v173, v173
	v_rcp_f32_e32 v176, v176
	v_rcp_f32_e32 v177, v177
	v_rcp_f32_e32 v180, v180
	v_rcp_f32_e32 v181, v181
	v_rcp_f32_e32 v184, v184
	v_rcp_f32_e32 v185, v185
	v_pk_mul_f32 v[44:45], v[44:45], v[152:153]
	v_pk_mul_f32 v[46:47], v[46:47], v[160:161]
	v_pk_mul_f32 v[40:41], v[40:41], v[164:165]
	v_pk_mul_f32 v[42:43], v[42:43], v[168:169]
	v_pk_mul_f32 v[36:37], v[36:37], v[172:173]
	v_pk_mul_f32 v[38:39], v[38:39], v[176:177]
	v_pk_mul_f32 v[32:33], v[32:33], v[180:181]
	v_pk_mul_f32 v[34:35], v[34:35], v[184:185]
	v_pk_mul_f32 v[222:223], v[44:45], v[44:45]
	v_pk_add_f32 v[220:221], v[44:45], v[46:47]
	v_pk_fma_f32 v[222:223], v[46:47], v[46:47], v[222:223]
	v_pk_fma_f32 v[222:223], v[40:41], v[40:41], v[222:223]
	v_pk_add_f32 v[220:221], v[220:221], v[40:41]
	v_pk_fma_f32 v[222:223], v[42:43], v[42:43], v[222:223]
	v_pk_add_f32 v[220:221], v[220:221], v[42:43]
	v_pk_fma_f32 v[222:223], v[36:37], v[36:37], v[222:223]
	v_pk_add_f32 v[220:221], v[220:221], v[36:37]
	v_pk_fma_f32 v[222:223], v[38:39], v[38:39], v[222:223]
	v_pk_add_f32 v[220:221], v[220:221], v[38:39]
	v_pk_fma_f32 v[222:223], v[32:33], v[32:33], v[222:223]
	v_pk_add_f32 v[220:221], v[220:221], v[32:33]
	v_pk_fma_f32 v[222:223], v[34:35], v[34:35], v[222:223]
	v_pk_add_f32 v[220:221], v[220:221], v[34:35]
	v_add_f32_e32 v202, v220, v221
	v_add_f32_e32 v203, v222, v223
	v_cvt_pk_bf16_f32 v44, v44, v45
	v_cvt_pk_bf16_f32 v45, v46, v47
	v_cvt_pk_bf16_f32 v46, v40, v41
	v_cvt_pk_bf16_f32 v47, v42, v43
	v_mad_i64_i32 v[216:217], s[90:91], v233, s80, v[212:213]
	v_lshl_add_u64 v[216:217], v[216:217], 0, v[210:211]
	global_store_dwordx4 v[216:217], v[44:47], off
	v_cvt_pk_bf16_f32 v36, v36, v37
	v_cvt_pk_bf16_f32 v37, v38, v39
	v_cvt_pk_bf16_f32 v38, v32, v33
	v_cvt_pk_bf16_f32 v39, v34, v35
	global_store_dwordx4 v[216:217], v[36:39], off offset:256
	v_pk_mul_f32 v[28:29], v[28:29], v[232:233] op_sel_hi:[1,0]
	v_pk_mul_f32 v[30:31], v[30:31], v[232:233] op_sel_hi:[1,0]
	v_pk_mul_f32 v[24:25], v[24:25], v[232:233] op_sel_hi:[1,0]
	v_pk_mul_f32 v[26:27], v[26:27], v[232:233] op_sel_hi:[1,0]
	v_pk_mul_f32 v[20:21], v[20:21], v[232:233] op_sel_hi:[1,0]
	v_pk_mul_f32 v[22:23], v[22:23], v[232:233] op_sel_hi:[1,0]
	v_pk_mul_f32 v[16:17], v[16:17], v[232:233] op_sel_hi:[1,0]
	v_pk_mul_f32 v[18:19], v[18:19], v[232:233] op_sel_hi:[1,0]
	v_pk_mul_f32 v[152:153], v[28:29], v[28:29]
; __device__ __forceinline__ unsigned cvt_pk_bf16(float lo, float hi) { unsigned r; asm volatile("v_cvt_pk_bf16_f32 %0, %1, %2" : "=v"(r) : "v"(lo), "v"(hi)); return r; }
; __device__ __forceinline__ float fast_rcp(float x) { return __builtin_amdgcn_rcpf(x); }
; __device__ __forceinline__ unsigned cvt_pk_bf16(float lo, float hi) { const f32x2 v = {lo, hi}; const bf16x2_t b = __builtin_convertvector(v, bf16x2_t); return __builtin_bit_cast(unsigned, b); }
;     __device__ __forceinline__ void operator()(const f32x4 (&acc)[2][2][4][2], const Unit& u, int wr, int wc, int fr, int fq) const {
;     ...
;                 for (int bj = 0; bj < 2; ++bj) {
;                     f32x4 a = acc[ai][bj][m][0] * rs, b = acc[ai][bj][m][1] * rs;
;                     if (u.pn < gelu_tiles) {
; #pragma unroll
;                         for (int j = 0; j < 4; ++j) { const float ua = 1.5957691216057308f * a[j] * (1.0f + 0.044715f * a[j] * a[j]), ub = 1.5957691216057308f * b[j] * (1.0f + 0.044715f * b[j] * b[j]);
;                             a[j] = a[j] * fast_rcp(1.0f + __expf(-ua)); b[j] = b[j] * fast_rcp(1.0f + __expf(-ub)); }
;                     }
;                     if (va_tile) {
;                         s1 += ((a[0] + a[1]) + (a[2] + a[3])) + ((b[0] + b[1]) + (b[2] + b[3]));
;                         s2 += ((a[0] * a[0] + a[1] * a[1]) + (a[2] * a[2] + a[3] * a[3])) + ((b[0] * b[0] + b[1] * b[1]) + (b[2] * b[2] + b[3] * b[3]));
;                     }
;                     u32x4 w; w.x = cvt_pk_bf16(a[0], a[1]); w.y = cvt_pk_bf16(a[2], a[3]); w.z = cvt_pk_bf16(b[0], b[1]); w.w = cvt_pk_bf16(b[2], b[3]);
;                     *(u32x4*)(O + (size_t)r * ldo + col0 + bj * HALF) = w;
	v_pk_mul_f32 v[160:161], v[30:31], v[30:31]
	v_pk_mul_f32 v[164:165], v[24:25], v[24:25]
	v_pk_mul_f32 v[168:169], v[26:27], v[26:27]
	v_pk_mul_f32 v[172:173], v[20:21], v[20:21]
	v_pk_mul_f32 v[176:177], v[22:23], v[22:23]
	v_pk_mul_f32 v[180:181], v[16:17], v[16:17]
	v_pk_mul_f32 v[184:185], v[18:19], v[18:19]
	v_pk_fma_f32 v[152:153], v[152:153], v[218:219], v[218:219] op_sel:[0,0,1] op_sel_hi:[1,0,1]
	v_pk_fma_f32 v[160:161], v[160:161], v[218:219], v[218:219] op_sel:[0,0,1] op_sel_hi:[1,0,1]
	v_pk_fma_f32 v[164:165], v[164:165], v[218:219], v[218:219] op_sel:[0,0,1] op_sel_hi:[1,0,1]
	v_pk_fma_f32 v[168:169], v[168:169], v[218:219], v[218:219] op_sel:[0,0,1] op_sel_hi:[1,0,1]
	v_pk_fma_f32 v[172:173], v[172:173], v[218:219], v[218:219] op_sel:[0,0,1] op_sel_hi:[1,0,1]
	v_pk_fma_f32 v[176:177], v[176:177], v[218:219], v[218:219] op_sel:[0,0,1] op_sel_hi:[1,0,1]
	v_pk_fma_f32 v[180:181], v[180:181], v[218:219], v[218:219] op_sel:[0,0,1] op_sel_hi:[1,0,1]
	v_pk_fma_f32 v[184:185], v[184:185], v[218:219], v[218:219] op_sel:[0,0,1] op_sel_hi:[1,0,1]
	v_pk_mul_f32 v[152:153], v[152:153], v[28:29]
	v_pk_mul_f32 v[160:161], v[160:161], v[30:31]
	v_pk_mul_f32 v[164:165], v[164:165], v[24:25]
	v_pk_mul_f32 v[168:169], v[168:169], v[26:27]
	v_pk_mul_f32 v[172:173], v[172:173], v[20:21]
	v_pk_mul_f32 v[176:177], v[176:177], v[22:23]
	v_pk_mul_f32 v[180:181], v[180:181], v[16:17]
	v_pk_mul_f32 v[184:185], v[184:185], v[18:19]
	v_exp_f32_e32 v152, v152
	v_exp_f32_e32 v153, v153
	v_exp_f32_e32 v160, v160
	v_exp_f32_e32 v161, v161
	v_exp_f32_e32 v164, v164
	v_exp_f32_e32 v165, v165
	v_exp_f32_e32 v168, v168
	v_exp_f32_e32 v169, v169
	v_exp_f32_e32 v172, v172
	v_exp_f32_e32 v173, v173
	v_exp_f32_e32 v176, v176
	v_exp_f32_e32 v177, v177
	v_exp_f32_e32 v180, v180
	v_exp_f32_e32 v181, v181
	v_exp_f32_e32 v184, v184
	v_exp_f32_e32 v185, v185
	v_pk_add_f32 v[152:153], v[152:153], 1.0 op_sel_hi:[1,0]
	v_pk_add_f32 v[160:161], v[160:161], 1.0 op_sel_hi:[1,0]
	v_pk_add_f32 v[164:165], v[164:165], 1.0 op_sel_hi:[1,0]
	v_pk_add_f32 v[168:169], v[168:169], 1.0 op_sel_hi:[1,0]
	v_pk_add_f32 v[172:173], v[172:173], 1.0 op_sel_hi:[1,0]
	v_pk_add_f32 v[176:177], v[176:177], 1.0 op_sel_hi:[1,0]
	v_pk_add_f32 v[180:181], v[180:181], 1.0 op_sel_hi:[1,0]
	v_pk_add_f32 v[184:185], v[184:185], 1.0 op_sel_hi:[1,0]
	v_rcp_f32_e32 v152, v152
	v_rcp_f32_e32 v153, v153
	v_rcp_f32_e32 v160, v160
	v_rcp_f32_e32 v161, v161
	v_rcp_f32_e32 v164, v164
	v_rcp_f32_e32 v165, v165
	v_rcp_f32_e32 v168, v168
	v_rcp_f32_e32 v169, v169
	v_rcp_f32_e32 v172, v172
	v_rcp_f32_e32 v173, v173
	v_rcp_f32_e32 v176, v176
	v_rcp_f32_e32 v177, v177
	v_rcp_f32_e32 v180, v180
	v_rcp_f32_e32 v181, v181
	v_rcp_f32_e32 v184, v184
	v_rcp_f32_e32 v185, v185
	v_pk_mul_f32 v[28:29], v[28:29], v[152:153]
	v_pk_mul_f32 v[30:31], v[30:31], v[160:161]
	v_pk_mul_f32 v[24:25], v[24:25], v[164:165]
	v_pk_mul_f32 v[26:27], v[26:27], v[168:169]
	v_pk_mul_f32 v[20:21], v[20:21], v[172:173]
	v_pk_mul_f32 v[22:23], v[22:23], v[176:177]
	v_pk_mul_f32 v[16:17], v[16:17], v[180:181]
	v_pk_mul_f32 v[18:19], v[18:19], v[184:185]
	v_pk_mul_f32 v[222:223], v[28:29], v[28:29]
	v_pk_add_f32 v[220:221], v[28:29], v[30:31]
	v_pk_fma_f32 v[222:223], v[30:31], v[30:31], v[222:223]
	v_pk_fma_f32 v[222:223], v[24:25], v[24:25], v[222:223]
	v_pk_add_f32 v[220:221], v[220:221], v[24:25]
	v_pk_fma_f32 v[222:223], v[26:27], v[26:27], v[222:223]
	v_pk_add_f32 v[220:221], v[220:221], v[26:27]
	v_pk_fma_f32 v[222:223], v[20:21], v[20:21], v[222:223]
	v_pk_add_f32 v[220:221], v[220:221], v[20:21]
	v_pk_fma_f32 v[222:223], v[22:23], v[22:23], v[222:223]
	v_pk_add_f32 v[220:221], v[220:221], v[22:23]
	v_pk_fma_f32 v[222:223], v[16:17], v[16:17], v[222:223]
	v_pk_add_f32 v[220:221], v[220:221], v[16:17]
	v_pk_fma_f32 v[222:223], v[18:19], v[18:19], v[222:223]
	v_pk_add_f32 v[220:221], v[220:221], v[18:19]
	v_add_f32_e32 v204, v220, v221
	v_add_f32_e32 v205, v222, v223
	v_cvt_pk_bf16_f32 v28, v28, v29
	v_cvt_pk_bf16_f32 v29, v30, v31
	v_cvt_pk_bf16_f32 v30, v24, v25
	v_cvt_pk_bf16_f32 v31, v26, v27
	v_mad_i64_i32 v[216:217], s[90:91], v235, s80, v[212:213]
	v_lshl_add_u64 v[216:217], v[216:217], 0, v[210:211]
	global_store_dwordx4 v[216:217], v[28:31], off
	v_cvt_pk_bf16_f32 v20, v20, v21
	v_cvt_pk_bf16_f32 v21, v22, v23
	v_cvt_pk_bf16_f32 v22, v16, v17
	v_cvt_pk_bf16_f32 v23, v18, v19
	global_store_dwordx4 v[216:217], v[20:23], off offset:256
	v_pk_mul_f32 v[12:13], v[12:13], v[234:235] op_sel_hi:[1,0]
	v_pk_mul_f32 v[14:15], v[14:15], v[234:235] op_sel_hi:[1,0]
	v_pk_mul_f32 v[8:9], v[8:9], v[234:235] op_sel_hi:[1,0]
	v_pk_mul_f32 v[10:11], v[10:11], v[234:235] op_sel_hi:[1,0]
	v_pk_mul_f32 v[4:5], v[4:5], v[234:235] op_sel_hi:[1,0]
	v_pk_mul_f32 v[6:7], v[6:7], v[234:235] op_sel_hi:[1,0]
	v_pk_mul_f32 v[0:1], v[0:1], v[234:235] op_sel_hi:[1,0]
	v_pk_mul_f32 v[2:3], v[2:3], v[234:235] op_sel_hi:[1,0]
	v_pk_mul_f32 v[152:153], v[12:13], v[12:13]
	v_pk_mul_f32 v[160:161], v[14:15], v[14:15]
	v_pk_mul_f32 v[164:165], v[8:9], v[8:9]
	v_pk_mul_f32 v[168:169], v[10:11], v[10:11]
	v_pk_mul_f32 v[172:173], v[4:5], v[4:5]
	v_pk_mul_f32 v[176:177], v[6:7], v[6:7]
	v_pk_mul_f32 v[180:181], v[0:1], v[0:1]
	v_pk_mul_f32 v[184:185], v[2:3], v[2:3]
	v_pk_fma_f32 v[152:153], v[152:153], v[218:219], v[218:219] op_sel:[0,0,1] op_sel_hi:[1,0,1]
	v_pk_fma_f32 v[160:161], v[160:161], v[218:219], v[218:219] op_sel:[0,0,1] op_sel_hi:[1,0,1]
	v_pk_fma_f32 v[164:165], v[164:165], v[218:219], v[218:219] op_sel:[0,0,1] op_sel_hi:[1,0,1]
	v_pk_fma_f32 v[168:169], v[168:169], v[218:219], v[218:219] op_sel:[0,0,1] op_sel_hi:[1,0,1]
; __device__ __forceinline__ unsigned cvt_pk_bf16(float lo, float hi) { unsigned r; asm volatile("v_cvt_pk_bf16_f32 %0, %1, %2" : "=v"(r) : "v"(lo), "v"(hi)); return r; }
; __device__ __forceinline__ float fast_rcp(float x) { return __builtin_amdgcn_rcpf(x); }
; __device__ __forceinline__ unsigned cvt_pk_bf16(float lo, float hi) { const f32x2 v = {lo, hi}; const bf16x2_t b = __builtin_convertvector(v, bf16x2_t); return __builtin_bit_cast(unsigned, b); }
;     __device__ __forceinline__ void operator()(const f32x4 (&acc)[2][2][4][2], const Unit& u, int wr, int wc, int fr, int fq) const {
;     ...
;                 for (int bj = 0; bj < 2; ++bj) {
;                     f32x4 a = acc[ai][bj][m][0] * rs, b = acc[ai][bj][m][1] * rs;
;                     if (u.pn < gelu_tiles) {
; #pragma unroll
;                         for (int j = 0; j < 4; ++j) { const float ua = 1.5957691216057308f * a[j] * (1.0f + 0.044715f * a[j] * a[j]), ub = 1.5957691216057308f * b[j] * (1.0f + 0.044715f * b[j] * b[j]);
;                             a[j] = a[j] * fast_rcp(1.0f + __expf(-ua)); b[j] = b[j] * fast_rcp(1.0f + __expf(-ub)); }
;                     }
;                     if (va_tile) {
;                         s1 += ((a[0] + a[1]) + (a[2] + a[3])) + ((b[0] + b[1]) + (b[2] + b[3]));
;                         s2 += ((a[0] * a[0] + a[1] * a[1]) + (a[2] * a[2] + a[3] * a[3])) + ((b[0] * b[0] + b[1] * b[1]) + (b[2] * b[2] + b[3] * b[3]));
;                     }
;                     u32x4 w; w.x = cvt_pk_bf16(a[0], a[1]); w.y = cvt_pk_bf16(a[2], a[3]); w.z = cvt_pk_bf16(b[0], b[1]); w.w = cvt_pk_bf16(b[2], b[3]);
;                     *(u32x4*)(O + (size_t)r * ldo + col0 + bj * HALF) = w;
;                 }
;                 if (va_tile) {
;                     s1 += __shfl_xor(s1, 16); s1 += __shfl_xor(s1, 32); s2 += __shfl_xor(s2, 16); s2 += __shfl_xor(s2, 32);
;                     if (fq == 0) *(f32x2*)(VS + (size_t)r * 16 + ((u.pn - 2) * 4 + wc) * 2) = (f32x2){s1, s2};
;                 }
	v_pk_fma_f32 v[172:173], v[172:173], v[218:219], v[218:219] op_sel:[0,0,1] op_sel_hi:[1,0,1]
	v_pk_fma_f32 v[176:177], v[176:177], v[218:219], v[218:219] op_sel:[0,0,1] op_sel_hi:[1,0,1]
	v_pk_fma_f32 v[180:181], v[180:181], v[218:219], v[218:219] op_sel:[0,0,1] op_sel_hi:[1,0,1]
	v_pk_fma_f32 v[184:185], v[184:185], v[218:219], v[218:219] op_sel:[0,0,1] op_sel_hi:[1,0,1]
	v_pk_mul_f32 v[152:153], v[152:153], v[12:13]
	v_pk_mul_f32 v[160:161], v[160:161], v[14:15]
	v_pk_mul_f32 v[164:165], v[164:165], v[8:9]
	v_pk_mul_f32 v[168:169], v[168:169], v[10:11]
	v_pk_mul_f32 v[172:173], v[172:173], v[4:5]
	v_pk_mul_f32 v[176:177], v[176:177], v[6:7]
	v_pk_mul_f32 v[180:181], v[180:181], v[0:1]
	v_pk_mul_f32 v[184:185], v[184:185], v[2:3]
	v_exp_f32_e32 v152, v152
	v_exp_f32_e32 v153, v153
	v_exp_f32_e32 v160, v160
	v_exp_f32_e32 v161, v161
	v_exp_f32_e32 v164, v164
	v_exp_f32_e32 v165, v165
	v_exp_f32_e32 v168, v168
	v_exp_f32_e32 v169, v169
	v_exp_f32_e32 v172, v172
	v_exp_f32_e32 v173, v173
	v_exp_f32_e32 v176, v176
	v_exp_f32_e32 v177, v177
	v_exp_f32_e32 v180, v180
	v_exp_f32_e32 v181, v181
	v_exp_f32_e32 v184, v184
	v_exp_f32_e32 v185, v185
	v_pk_add_f32 v[152:153], v[152:153], 1.0 op_sel_hi:[1,0]
	v_pk_add_f32 v[160:161], v[160:161], 1.0 op_sel_hi:[1,0]
	v_pk_add_f32 v[164:165], v[164:165], 1.0 op_sel_hi:[1,0]
	v_pk_add_f32 v[168:169], v[168:169], 1.0 op_sel_hi:[1,0]
	v_pk_add_f32 v[172:173], v[172:173], 1.0 op_sel_hi:[1,0]
	v_pk_add_f32 v[176:177], v[176:177], 1.0 op_sel_hi:[1,0]
	v_pk_add_f32 v[180:181], v[180:181], 1.0 op_sel_hi:[1,0]
	v_pk_add_f32 v[184:185], v[184:185], 1.0 op_sel_hi:[1,0]
	v_rcp_f32_e32 v152, v152
	v_rcp_f32_e32 v153, v153
	v_rcp_f32_e32 v160, v160
	v_rcp_f32_e32 v161, v161
	v_rcp_f32_e32 v164, v164
	v_rcp_f32_e32 v165, v165
	v_rcp_f32_e32 v168, v168
	v_rcp_f32_e32 v169, v169
	v_rcp_f32_e32 v172, v172
	v_rcp_f32_e32 v173, v173
	v_rcp_f32_e32 v176, v176
	v_rcp_f32_e32 v177, v177
	v_rcp_f32_e32 v180, v180
	v_rcp_f32_e32 v181, v181
	v_rcp_f32_e32 v184, v184
	v_rcp_f32_e32 v185, v185
	v_pk_mul_f32 v[12:13], v[12:13], v[152:153]
	v_pk_mul_f32 v[14:15], v[14:15], v[160:161]
	v_pk_mul_f32 v[8:9], v[8:9], v[164:165]
	v_pk_mul_f32 v[10:11], v[10:11], v[168:169]
	v_pk_mul_f32 v[4:5], v[4:5], v[172:173]
	v_pk_mul_f32 v[6:7], v[6:7], v[176:177]
	v_pk_mul_f32 v[0:1], v[0:1], v[180:181]
	v_pk_mul_f32 v[2:3], v[2:3], v[184:185]
	v_pk_mul_f32 v[222:223], v[12:13], v[12:13]
	v_pk_add_f32 v[220:221], v[12:13], v[14:15]
	v_pk_fma_f32 v[222:223], v[14:15], v[14:15], v[222:223]
	v_pk_fma_f32 v[222:223], v[8:9], v[8:9], v[222:223]
	v_pk_add_f32 v[220:221], v[220:221], v[8:9]
	v_pk_fma_f32 v[222:223], v[10:11], v[10:11], v[222:223]
	v_pk_add_f32 v[220:221], v[220:221], v[10:11]
	v_pk_fma_f32 v[222:223], v[4:5], v[4:5], v[222:223]
	v_pk_add_f32 v[220:221], v[220:221], v[4:5]
	v_pk_fma_f32 v[222:223], v[6:7], v[6:7], v[222:223]
	v_pk_add_f32 v[220:221], v[220:221], v[6:7]
	v_pk_fma_f32 v[222:223], v[0:1], v[0:1], v[222:223]
	v_pk_add_f32 v[220:221], v[220:221], v[0:1]
	v_pk_fma_f32 v[222:223], v[2:3], v[2:3], v[222:223]
	v_pk_add_f32 v[220:221], v[220:221], v[2:3]
	v_add_f32_e32 v206, v220, v221
	v_add_f32_e32 v207, v222, v223
	v_cvt_pk_bf16_f32 v12, v12, v13
	v_cvt_pk_bf16_f32 v13, v14, v15
	v_cvt_pk_bf16_f32 v14, v8, v9
	v_cvt_pk_bf16_f32 v15, v10, v11
	v_mad_i64_i32 v[216:217], s[90:91], v236, s80, v[212:213]
	v_lshl_add_u64 v[216:217], v[216:217], 0, v[210:211]
	global_store_dwordx4 v[216:217], v[12:15], off
	v_cvt_pk_bf16_f32 v4, v4, v5
	v_cvt_pk_bf16_f32 v5, v6, v7
	v_cvt_pk_bf16_f32 v6, v0, v1
	v_cvt_pk_bf16_f32 v7, v2, v3
	global_store_dwordx4 v[216:217], v[4:7], off offset:256
	ds_bpermute_b32 v154, v237, v150
	ds_bpermute_b32 v162, v237, v156
	ds_bpermute_b32 v166, v237, v196
	ds_bpermute_b32 v170, v237, v198
	ds_bpermute_b32 v155, v237, v151
	ds_bpermute_b32 v163, v237, v157
	ds_bpermute_b32 v167, v237, v197
	ds_bpermute_b32 v171, v237, v199
	s_waitcnt lgkmcnt(3)
	v_pk_add_f32 v[150:151], v[150:151], v[154:155]
	s_waitcnt lgkmcnt(2)
	v_pk_add_f32 v[156:157], v[156:157], v[162:163]
	s_waitcnt lgkmcnt(1)
	v_pk_add_f32 v[196:197], v[196:197], v[166:167]
	s_waitcnt lgkmcnt(0)
	v_pk_add_f32 v[198:199], v[198:199], v[170:171]
	ds_bpermute_b32 v174, v237, v200
	ds_bpermute_b32 v178, v237, v202
	ds_bpermute_b32 v182, v237, v204
	ds_bpermute_b32 v186, v237, v206
	ds_bpermute_b32 v175, v237, v201
	ds_bpermute_b32 v179, v237, v203
	ds_bpermute_b32 v183, v237, v205
	ds_bpermute_b32 v187, v237, v207
	s_waitcnt lgkmcnt(3)
	v_pk_add_f32 v[200:201], v[200:201], v[174:175]
	s_waitcnt lgkmcnt(2)
	v_pk_add_f32 v[202:203], v[202:203], v[178:179]
	s_waitcnt lgkmcnt(1)
	v_pk_add_f32 v[204:205], v[204:205], v[182:183]
	s_waitcnt lgkmcnt(0)
	v_pk_add_f32 v[206:207], v[206:207], v[186:187]
	ds_bpermute_b32 v154, v238, v150
	ds_bpermute_b32 v162, v238, v156
	ds_bpermute_b32 v166, v238, v196
	ds_bpermute_b32 v170, v238, v198
	ds_bpermute_b32 v155, v238, v151
	ds_bpermute_b32 v163, v238, v157
	ds_bpermute_b32 v167, v238, v197
	ds_bpermute_b32 v171, v238, v199
	s_waitcnt lgkmcnt(3)
	v_pk_add_f32 v[150:151], v[150:151], v[154:155]
	s_waitcnt lgkmcnt(2)
	v_pk_add_f32 v[156:157], v[156:157], v[162:163]
	s_waitcnt lgkmcnt(1)
	v_pk_add_f32 v[196:197], v[196:197], v[166:167]
	s_waitcnt lgkmcnt(0)
	v_pk_add_f32 v[198:199], v[198:199], v[170:171]
	ds_bpermute_b32 v174, v238, v200
	ds_bpermute_b32 v178, v238, v202
	ds_bpermute_b32 v182, v238, v204
	ds_bpermute_b32 v186, v238, v206
	ds_bpermute_b32 v175, v238, v201
	ds_bpermute_b32 v179, v238, v203
	ds_bpermute_b32 v183, v238, v205
	ds_bpermute_b32 v187, v238, v207
	s_waitcnt lgkmcnt(3)
	v_pk_add_f32 v[200:201], v[200:201], v[174:175]
	s_waitcnt lgkmcnt(2)
	v_pk_add_f32 v[202:203], v[202:203], v[178:179]
	s_waitcnt lgkmcnt(1)
	v_pk_add_f32 v[204:205], v[204:205], v[182:183]
	s_waitcnt lgkmcnt(0)
	v_pk_add_f32 v[206:207], v[206:207], v[186:187]
	s_lshl_b32 s88, s22, 3
	s_add_i32 s88, s88, s74
	s_lshl_b32 s88, s88, 2
	s_mov_b32 s89, 0
	v_lshlrev_b32_e32 v214, 6, v208
	v_mov_b32_e32 v215, 0
	v_lshl_add_u64 v[214:215], s[40:41], 0, v[214:215]
	v_lshl_add_u64 v[214:215], v[214:215], 0, s[88:89]
	s_and_saveexec_b64 s[86:87], s[6:7]
	global_store_dwordx2 v[214:215], v[150:151], off
	global_store_dwordx2 v[214:215], v[156:157], off offset:1024
	global_store_dwordx2 v[214:215], v[196:197], off offset:2048
	global_store_dwordx2 v[214:215], v[198:199], off offset:3072
	v_lshl_add_u64 v[214:215], v[214:215], 0, s[84:85]
	global_store_dwordx2 v[214:215], v[200:201], off
	global_store_dwordx2 v[214:215], v[202:203], off offset:1024
	global_store_dwordx2 v[214:215], v[204:205], off offset:2048
	global_store_dwordx2 v[214:215], v[206:207], off offset:3072
	s_or_b64 exec, exec, s[86:87]
	s_branch .Lepiz_done_p3
; __device__ __forceinline__ unsigned cvt_pk_bf16(float lo, float hi) { unsigned r; asm volatile("v_cvt_pk_bf16_f32 %0, %1, %2" : "=v"(r) : "v"(lo), "v"(hi)); return r; }
; __device__ __forceinline__ float fast_rcp(float x) { return __builtin_amdgcn_rcpf(x); }
; __device__ __forceinline__ unsigned cvt_pk_bf16(float lo, float hi) { const f32x2 v = {lo, hi}; const bf16x2_t b = __builtin_convertvector(v, bf16x2_t); return __builtin_bit_cast(unsigned, b); }
;     __device__ __forceinline__ void operator()(const f32x4 (&acc)[2][2][4][2], const Unit& u, int wr, int wc, int fr, int fq) const {
;     ...
;                 const int r = row0 + ai * HALF + m * 16; const float rs = rsv[ai][m];
;                 float s1 = 0.f, s2 = 0.f;
; #pragma unroll
;                 for (int bj = 0; bj < 2; ++bj) {
;                     f32x4 a = acc[ai][bj][m][0] * rs, b = acc[ai][bj][m][1] * rs;
;                     if (u.pn < gelu_tiles) {
; #pragma unroll
;                         for (int j = 0; j < 4; ++j) { const float ua = 1.5957691216057308f * a[j] * (1.0f + 0.044715f * a[j] * a[j]), ub = 1.5957691216057308f * b[j] * (1.0f + 0.044715f * b[j] * b[j]);
;                             a[j] = a[j] * fast_rcp(1.0f + __expf(-ua)); b[j] = b[j] * fast_rcp(1.0f + __expf(-ub)); }
;                     }
;                     if (va_tile) {
;                         s1 += ((a[0] + a[1]) + (a[2] + a[3])) + ((b[0] + b[1]) + (b[2] + b[3]));
;                         s2 += ((a[0] * a[0] + a[1] * a[1]) + (a[2] * a[2] + a[3] * a[3])) + ((b[0] * b[0] + b[1] * b[1]) + (b[2] * b[2] + b[3] * b[3]));
;                     }
;                     u32x4 w; w.x = cvt_pk_bf16(a[0], a[1]); w.y = cvt_pk_bf16(a[2], a[3]); w.z = cvt_pk_bf16(b[0], b[1]); w.w = cvt_pk_bf16(b[2], b[3]);
;                     *(u32x4*)(O + (size_t)r * ldo + col0 + bj * HALF) = w;
.Lepiz_plain_p3:
	v_pk_mul_f32 v[124:125], v[124:125], v[128:129] op_sel_hi:[1,0]
	v_pk_mul_f32 v[126:127], v[126:127], v[128:129] op_sel_hi:[1,0]
	v_pk_mul_f32 v[120:121], v[120:121], v[128:129] op_sel_hi:[1,0]
	v_pk_mul_f32 v[122:123], v[122:123], v[128:129] op_sel_hi:[1,0]
	v_pk_mul_f32 v[116:117], v[116:117], v[128:129] op_sel_hi:[1,0]
	v_pk_mul_f32 v[118:119], v[118:119], v[128:129] op_sel_hi:[1,0]
	v_pk_mul_f32 v[112:113], v[112:113], v[128:129] op_sel_hi:[1,0]
	v_pk_mul_f32 v[114:115], v[114:115], v[128:129] op_sel_hi:[1,0]
	v_cvt_pk_bf16_f32 v124, v124, v125
	v_cvt_pk_bf16_f32 v125, v126, v127
	v_cvt_pk_bf16_f32 v126, v120, v121
	v_cvt_pk_bf16_f32 v127, v122, v123
	v_mad_i64_i32 v[216:217], s[90:91], v208, s80, v[212:213]
	v_lshl_add_u64 v[216:217], v[216:217], 0, v[210:211]
	global_store_dwordx4 v[216:217], v[124:127], off
	v_cvt_pk_bf16_f32 v116, v116, v117
	v_cvt_pk_bf16_f32 v117, v118, v119
	v_cvt_pk_bf16_f32 v118, v112, v113
	v_cvt_pk_bf16_f32 v119, v114, v115
	global_store_dwordx4 v[216:217], v[116:119], off offset:256
	v_pk_mul_f32 v[108:109], v[108:109], v[158:159] op_sel_hi:[1,0]
	v_pk_mul_f32 v[110:111], v[110:111], v[158:159] op_sel_hi:[1,0]
	v_pk_mul_f32 v[104:105], v[104:105], v[158:159] op_sel_hi:[1,0]
	v_pk_mul_f32 v[106:107], v[106:107], v[158:159] op_sel_hi:[1,0]
	v_pk_mul_f32 v[100:101], v[100:101], v[158:159] op_sel_hi:[1,0]
	v_pk_mul_f32 v[102:103], v[102:103], v[158:159] op_sel_hi:[1,0]
	v_pk_mul_f32 v[96:97], v[96:97], v[158:159] op_sel_hi:[1,0]
	v_pk_mul_f32 v[98:99], v[98:99], v[158:159] op_sel_hi:[1,0]
	v_cvt_pk_bf16_f32 v108, v108, v109
	v_cvt_pk_bf16_f32 v109, v110, v111
	v_cvt_pk_bf16_f32 v110, v104, v105
	v_cvt_pk_bf16_f32 v111, v106, v107
	v_mad_i64_i32 v[216:217], s[90:91], v225, s80, v[212:213]
	v_lshl_add_u64 v[216:217], v[216:217], 0, v[210:211]
	global_store_dwordx4 v[216:217], v[108:111], off
	v_cvt_pk_bf16_f32 v100, v100, v101
	v_cvt_pk_bf16_f32 v101, v102, v103
	v_cvt_pk_bf16_f32 v102, v96, v97
	v_cvt_pk_bf16_f32 v103, v98, v99
	global_store_dwordx4 v[216:217], v[100:103], off offset:256
	v_pk_mul_f32 v[92:93], v[92:93], v[224:225] op_sel_hi:[1,0]
	v_pk_mul_f32 v[94:95], v[94:95], v[224:225] op_sel_hi:[1,0]
	v_pk_mul_f32 v[88:89], v[88:89], v[224:225] op_sel_hi:[1,0]
	v_pk_mul_f32 v[90:91], v[90:91], v[224:225] op_sel_hi:[1,0]
	v_pk_mul_f32 v[84:85], v[84:85], v[224:225] op_sel_hi:[1,0]
	v_pk_mul_f32 v[86:87], v[86:87], v[224:225] op_sel_hi:[1,0]
	v_pk_mul_f32 v[80:81], v[80:81], v[224:225] op_sel_hi:[1,0]
	v_pk_mul_f32 v[82:83], v[82:83], v[224:225] op_sel_hi:[1,0]
	v_cvt_pk_bf16_f32 v92, v92, v93
	v_cvt_pk_bf16_f32 v93, v94, v95
	v_cvt_pk_bf16_f32 v94, v88, v89
	v_cvt_pk_bf16_f32 v95, v90, v91
	v_mad_i64_i32 v[216:217], s[90:91], v227, s80, v[212:213]
	v_lshl_add_u64 v[216:217], v[216:217], 0, v[210:211]
	global_store_dwordx4 v[216:217], v[92:95], off
	v_cvt_pk_bf16_f32 v84, v84, v85
	v_cvt_pk_bf16_f32 v85, v86, v87
	v_cvt_pk_bf16_f32 v86, v80, v81
	v_cvt_pk_bf16_f32 v87, v82, v83
	global_store_dwordx4 v[216:217], v[84:87], off offset:256
	v_pk_mul_f32 v[76:77], v[76:77], v[226:227] op_sel_hi:[1,0]
	v_pk_mul_f32 v[78:79], v[78:79], v[226:227] op_sel_hi:[1,0]
	v_pk_mul_f32 v[72:73], v[72:73], v[226:227] op_sel_hi:[1,0]
	v_pk_mul_f32 v[74:75], v[74:75], v[226:227] op_sel_hi:[1,0]
	v_pk_mul_f32 v[68:69], v[68:69], v[226:227] op_sel_hi:[1,0]
	v_pk_mul_f32 v[70:71], v[70:71], v[226:227] op_sel_hi:[1,0]
	v_pk_mul_f32 v[64:65], v[64:65], v[226:227] op_sel_hi:[1,0]
	v_pk_mul_f32 v[66:67], v[66:67], v[226:227] op_sel_hi:[1,0]
	v_cvt_pk_bf16_f32 v76, v76, v77
	v_cvt_pk_bf16_f32 v77, v78, v79
	v_cvt_pk_bf16_f32 v78, v72, v73
	v_cvt_pk_bf16_f32 v79, v74, v75
	v_mad_i64_i32 v[216:217], s[90:91], v229, s80, v[212:213]
	v_lshl_add_u64 v[216:217], v[216:217], 0, v[210:211]
	global_store_dwordx4 v[216:217], v[76:79], off
	v_cvt_pk_bf16_f32 v68, v68, v69
	v_cvt_pk_bf16_f32 v69, v70, v71
	v_cvt_pk_bf16_f32 v70, v64, v65
	v_cvt_pk_bf16_f32 v71, v66, v67
	global_store_dwordx4 v[216:217], v[68:71], off offset:256
	v_pk_mul_f32 v[60:61], v[60:61], v[228:229] op_sel_hi:[1,0]
; __device__ __forceinline__ unsigned cvt_pk_bf16(float lo, float hi) { unsigned r; asm volatile("v_cvt_pk_bf16_f32 %0, %1, %2" : "=v"(r) : "v"(lo), "v"(hi)); return r; }
; __device__ __forceinline__ unsigned cvt_pk_bf16(float lo, float hi) { const f32x2 v = {lo, hi}; const bf16x2_t b = __builtin_convertvector(v, bf16x2_t); return __builtin_bit_cast(unsigned, b); }
;     __device__ __forceinline__ void operator()(const f32x4 (&acc)[2][2][4][2], const Unit& u, int wr, int wc, int fr, int fq) const {
;     ...
;                     u32x4 w; w.x = cvt_pk_bf16(a[0], a[1]); w.y = cvt_pk_bf16(a[2], a[3]); w.z = cvt_pk_bf16(b[0], b[1]); w.w = cvt_pk_bf16(b[2], b[3]);
;                     *(u32x4*)(O + (size_t)r * ldo + col0 + bj * HALF) = w;
;                 }
;                 if (va_tile) {
;                     s1 += __shfl_xor(s1, 16); s1 += __shfl_xor(s1, 32); s2 += __shfl_xor(s2, 16); s2 += __shfl_xor(s2, 32);
;                     if (fq == 0) *(f32x2*)(VS + (size_t)r * 16 + ((u.pn - 2) * 4 + wc) * 2) = (f32x2){s1, s2};
;                 }
;             }
	v_pk_mul_f32 v[62:63], v[62:63], v[228:229] op_sel_hi:[1,0]
	v_pk_mul_f32 v[56:57], v[56:57], v[228:229] op_sel_hi:[1,0]
	v_pk_mul_f32 v[58:59], v[58:59], v[228:229] op_sel_hi:[1,0]
	v_pk_mul_f32 v[52:53], v[52:53], v[228:229] op_sel_hi:[1,0]
	v_pk_mul_f32 v[54:55], v[54:55], v[228:229] op_sel_hi:[1,0]
	v_pk_mul_f32 v[48:49], v[48:49], v[228:229] op_sel_hi:[1,0]
	v_pk_mul_f32 v[50:51], v[50:51], v[228:229] op_sel_hi:[1,0]
	v_cvt_pk_bf16_f32 v60, v60, v61
	v_cvt_pk_bf16_f32 v61, v62, v63
	v_cvt_pk_bf16_f32 v62, v56, v57
	v_cvt_pk_bf16_f32 v63, v58, v59
	v_mad_i64_i32 v[216:217], s[90:91], v231, s80, v[212:213]
	v_lshl_add_u64 v[216:217], v[216:217], 0, v[210:211]
	global_store_dwordx4 v[216:217], v[60:63], off
	v_cvt_pk_bf16_f32 v52, v52, v53
	v_cvt_pk_bf16_f32 v53, v54, v55
	v_cvt_pk_bf16_f32 v54, v48, v49
	v_cvt_pk_bf16_f32 v55, v50, v51
	global_store_dwordx4 v[216:217], v[52:55], off offset:256
	v_pk_mul_f32 v[44:45], v[44:45], v[230:231] op_sel_hi:[1,0]
	v_pk_mul_f32 v[46:47], v[46:47], v[230:231] op_sel_hi:[1,0]
	v_pk_mul_f32 v[40:41], v[40:41], v[230:231] op_sel_hi:[1,0]
	v_pk_mul_f32 v[42:43], v[42:43], v[230:231] op_sel_hi:[1,0]
	v_pk_mul_f32 v[36:37], v[36:37], v[230:231] op_sel_hi:[1,0]
	v_pk_mul_f32 v[38:39], v[38:39], v[230:231] op_sel_hi:[1,0]
	v_pk_mul_f32 v[32:33], v[32:33], v[230:231] op_sel_hi:[1,0]
	v_pk_mul_f32 v[34:35], v[34:35], v[230:231] op_sel_hi:[1,0]
	v_cvt_pk_bf16_f32 v44, v44, v45
	v_cvt_pk_bf16_f32 v45, v46, v47
	v_cvt_pk_bf16_f32 v46, v40, v41
	v_cvt_pk_bf16_f32 v47, v42, v43
	v_mad_i64_i32 v[216:217], s[90:91], v233, s80, v[212:213]
	v_lshl_add_u64 v[216:217], v[216:217], 0, v[210:211]
	global_store_dwordx4 v[216:217], v[44:47], off
	v_cvt_pk_bf16_f32 v36, v36, v37
	v_cvt_pk_bf16_f32 v37, v38, v39
	v_cvt_pk_bf16_f32 v38, v32, v33
	v_cvt_pk_bf16_f32 v39, v34, v35
	global_store_dwordx4 v[216:217], v[36:39], off offset:256
	v_pk_mul_f32 v[28:29], v[28:29], v[232:233] op_sel_hi:[1,0]
	v_pk_mul_f32 v[30:31], v[30:31], v[232:233] op_sel_hi:[1,0]
	v_pk_mul_f32 v[24:25], v[24:25], v[232:233] op_sel_hi:[1,0]
	v_pk_mul_f32 v[26:27], v[26:27], v[232:233] op_sel_hi:[1,0]
	v_pk_mul_f32 v[20:21], v[20:21], v[232:233] op_sel_hi:[1,0]
	v_pk_mul_f32 v[22:23], v[22:23], v[232:233] op_sel_hi:[1,0]
	v_pk_mul_f32 v[16:17], v[16:17], v[232:233] op_sel_hi:[1,0]
	v_pk_mul_f32 v[18:19], v[18:19], v[232:233] op_sel_hi:[1,0]
	v_cvt_pk_bf16_f32 v28, v28, v29
	v_cvt_pk_bf16_f32 v29, v30, v31
	v_cvt_pk_bf16_f32 v30, v24, v25
	v_cvt_pk_bf16_f32 v31, v26, v27
	v_mad_i64_i32 v[216:217], s[90:91], v235, s80, v[212:213]
	v_lshl_add_u64 v[216:217], v[216:217], 0, v[210:211]
	global_store_dwordx4 v[216:217], v[28:31], off
	v_cvt_pk_bf16_f32 v20, v20, v21
	v_cvt_pk_bf16_f32 v21, v22, v23
	v_cvt_pk_bf16_f32 v22, v16, v17
	v_cvt_pk_bf16_f32 v23, v18, v19
	global_store_dwordx4 v[216:217], v[20:23], off offset:256
	v_pk_mul_f32 v[12:13], v[12:13], v[234:235] op_sel_hi:[1,0]
	v_pk_mul_f32 v[14:15], v[14:15], v[234:235] op_sel_hi:[1,0]
	v_pk_mul_f32 v[8:9], v[8:9], v[234:235] op_sel_hi:[1,0]
	v_pk_mul_f32 v[10:11], v[10:11], v[234:235] op_sel_hi:[1,0]
	v_pk_mul_f32 v[4:5], v[4:5], v[234:235] op_sel_hi:[1,0]
	v_pk_mul_f32 v[6:7], v[6:7], v[234:235] op_sel_hi:[1,0]
	v_pk_mul_f32 v[0:1], v[0:1], v[234:235] op_sel_hi:[1,0]
	v_pk_mul_f32 v[2:3], v[2:3], v[234:235] op_sel_hi:[1,0]
	v_cvt_pk_bf16_f32 v12, v12, v13
	v_cvt_pk_bf16_f32 v13, v14, v15
	v_cvt_pk_bf16_f32 v14, v8, v9
	v_cvt_pk_bf16_f32 v15, v10, v11
	v_mad_i64_i32 v[216:217], s[90:91], v236, s80, v[212:213]
	v_lshl_add_u64 v[216:217], v[216:217], 0, v[210:211]
	global_store_dwordx4 v[216:217], v[12:15], off
	v_cvt_pk_bf16_f32 v4, v4, v5
	v_cvt_pk_bf16_f32 v5, v6, v7
	v_cvt_pk_bf16_f32 v6, v0, v1
	v_cvt_pk_bf16_f32 v7, v2, v3
	global_store_dwordx4 v[216:217], v[4:7], off offset:256
.Lepiz_done_p3:
	v_xor_b32_e32 v139, 32, v194
.LBB0_610:
	s_and_b64 vcc, exec, s[8:9]
	s_mov_b64 s[8:9], -1
	s_cbranch_vccnz .LBB0_460
	s_andn2_b64 vcc, exec, s[36:37]
	s_cbranch_vccnz .LBB0_459
	s_barrier
	s_branch .LBB0_459
.LBB0_615:
	s_waitcnt vmcnt(0)
	s_barrier
	s_andn2_b64 vcc, exec, s[54:55]
	s_cbranch_vccnz .LBB0_640
